# opt22: GEMM k-loops: loop-control SALU (counter, pointer bumps, exit compare) moved ahead of the loop-back barrier (back-edge rotation)
# speedup vs baseline: 1.0062x; 1.0062x over previous
; #define PG8_STAGE(bufoff, gbase, voff) do { _Pragma("unroll") for (int _i = 0; _i < 2; ++_i) \
;         __builtin_amdgcn_global_load_lds((const unsigned*)((const char*)(gbase) + (voff)[_i]), (PG8_LAS unsigned*)(lds + (bufoff) + ldsw + _i * 8192), 16, 0, 0); } while (0)
; #define PG8_LDA(dst, b, h) do { _Pragma("unroll") for (int m = 0; m < 4; ++m) _Pragma("unroll") for (int k = 0; k < 2; ++k) dst[m][k] = *(const PG8_LAS half8*)(lds + PG8_SA(b, h) + aoff + m * 2048 + k * 1024); } while (0)
; #define PG8_LDB(dst, b, h) do { _Pragma("unroll") for (int n = 0; n < 2; ++n) _Pragma("unroll") for (int k = 0; k < 2; ++k) dst[n][k] = *(const PG8_LAS half8*)(lds + PG8_SB(b, h) + boff + n * 2048 + k * 1024); } while (0)
; #define PG8_MMA(ai, bj, At, Bt) do { __builtin_amdgcn_s_setprio(1); _Pragma("unroll") for (int m = 0; m < 4; ++m) _Pragma("unroll") for (int n = 0; n < 2; ++n) _Pragma("unroll") for (int k = 0; k < 2; ++k) \
;         acc[ai][bj][m][n] = __builtin_amdgcn_mfma_f32_16x16x32_f16(Bt[n][k], At[m][k], acc[ai][bj][m][n], 0, 0, 0); __builtin_amdgcn_s_setprio(0); } while (0)
; #define PG8_WAIT_V(n) asm volatile("s_waitcnt vmcnt(" #n ")" ::: "memory")
; #define PG8_WAIT_L(n) asm volatile("s_waitcnt lgkmcnt(" #n ")" ::: "memory")
; #define PG8_BAR __builtin_amdgcn_s_barrier()
; #define PG8_SCHED __builtin_amdgcn_sched_barrier(0)
; template <class Epi>
; __device__ __forceinline__ void gemm_phase(PG8_LAS unsigned char* lds, const Gemm g, const StaticOrder& S_, const Epi& E) {
;     ...
;         for (int t = 0; t < nt; t += 2) {
;             const bool last = (t == nt - 2);
;             const char* a1 = cA + (size_t)(t + 1) * kstep;
;             const char* a2 = last ? nA : cA + (size_t)(t + 2) * kstep; const char* b2 = last ? nB : cB + (size_t)(t + 2) * kstep;
;             const char* a3 = a2 + kstep; const char* b3 = b2 + kstep;
;             PG8_LDB(B0, 0, 0); PG8_LDB(B1, 0, 1); PG8_SCHED; PG8_LDA(At, 0, 0); PG8_STAGE(PG8_SA(1, 1), a1 + hstepA, voffA);
;             PG8_WAIT_V(8); PG8_WAIT_L(0); PG8_BAR; PG8_MMA(0, 0, At, B0); PG8_MMA(0, 1, At, B1); PG8_BAR; PG8_SCHED;
;             PG8_LDA(At, 0, 1); PG8_STAGE(PG8_SB(0, 0), b2, voffB); PG8_STAGE(PG8_SB(0, 1), b2 + hstepB, voffB); PG8_STAGE(PG8_SA(0, 0), a2, voffA);
;             PG8_WAIT_V(8); PG8_WAIT_L(0); PG8_BAR; PG8_MMA(1, 0, At, B0); PG8_MMA(1, 1, At, B1); PG8_BAR; PG8_SCHED;
.LBB0_183:
	s_add_u32 s2, s10, 0xfffc0080
	s_addc_u32 s3, s11, -1
	s_add_i32 s19, 0, 0x10000
	s_cmp_eq_u32 s18, 12
	s_cselect_b32 s13, s7, s3
	s_cselect_b32 s12, s9, s2
	v_add_u32_e32 v0, s19, v187
	s_cselect_b32 s3, s14, s17
	s_cselect_b32 s2, s15, s16
	s_add_i32 s33, 0, 0x14000
	ds_read_b128 v[130:133], v0
	ds_read_b128 v[134:137], v0 offset:1024
	ds_read_b128 v[138:141], v0 offset:2048
	ds_read_b128 v[160:163], v0 offset:3072
	v_add_u32_e32 v0, s33, v187
	ds_read_b128 v[164:167], v0
	ds_read_b128 v[180:183], v0 offset:1024
	ds_read_b128 v[208:211], v0 offset:2048
	ds_read_b128 v[212:215], v0 offset:3072
	v_lshl_add_u64 v[168:169], s[10:11], 0, v[158:159]
	s_add_i32 m0, s60, 0xc000
	ds_read_b128 v[216:219], v194
	ds_read_b128 v[220:223], v194 offset:1024
	ds_read_b128 v[224:227], v194 offset:2048
	ds_read_b128 v[228:231], v194 offset:3072
	ds_read_b128 v[232:235], v194 offset:4096
	ds_read_b128 v[236:239], v194 offset:5120
	ds_read_b128 v[240:243], v194 offset:6144
	ds_read_b128 v[244:247], v194 offset:7168
	global_load_lds_dwordx4 v[168:169], off
	v_lshl_add_u64 v[168:169], s[10:11], 0, v[156:157]
	s_add_i32 m0, s60, 0xe000
	s_nop 0
	global_load_lds_dwordx4 v[168:169], off
	s_waitcnt vmcnt(8)
	s_waitcnt lgkmcnt(0)
	s_barrier
	s_setprio 1
	s_waitcnt lgkmcnt(0)
	v_mfma_f32_16x16x32_f16 v[126:129], v[130:133], v[216:219], v[126:129]
	v_mfma_f32_16x16x32_f16 v[114:117], v[138:141], v[216:219], v[114:117]
	v_mfma_f32_16x16x32_f16 v[122:125], v[130:133], v[224:227], v[122:125]
	v_mfma_f32_16x16x32_f16 v[106:109], v[138:141], v[224:227], v[106:109]
	v_mfma_f32_16x16x32_f16 v[118:121], v[130:133], v[232:235], v[118:121]
	v_mfma_f32_16x16x32_f16 v[102:105], v[138:141], v[232:235], v[102:105]
	v_mfma_f32_16x16x32_f16 v[110:113], v[130:133], v[240:243], v[110:113]
	v_mfma_f32_16x16x32_f16 v[98:101], v[138:141], v[240:243], v[98:101]
	v_mfma_f32_16x16x32_f16 v[126:129], v[134:137], v[220:223], v[126:129]
	v_mfma_f32_16x16x32_f16 v[114:117], v[160:163], v[220:223], v[114:117]
	v_mfma_f32_16x16x32_f16 v[122:125], v[134:137], v[228:231], v[122:125]
	v_mfma_f32_16x16x32_f16 v[106:109], v[160:163], v[228:231], v[106:109]
	v_mfma_f32_16x16x32_f16 v[118:121], v[134:137], v[236:239], v[118:121]
	v_mfma_f32_16x16x32_f16 v[102:105], v[160:163], v[236:239], v[102:105]
	v_mfma_f32_16x16x32_f16 v[110:113], v[134:137], v[244:247], v[110:113]
	v_mfma_f32_16x16x32_f16 v[98:101], v[160:163], v[244:247], v[98:101]
	s_setprio 0
	s_setprio 1
	v_mfma_f32_16x16x32_f16 v[62:65], v[164:167], v[216:219], v[62:65]
	v_mfma_f32_16x16x32_f16 v[50:53], v[208:211], v[216:219], v[50:53]
	v_mfma_f32_16x16x32_f16 v[58:61], v[164:167], v[224:227], v[58:61]
	v_mfma_f32_16x16x32_f16 v[42:45], v[208:211], v[224:227], v[42:45]
	v_mfma_f32_16x16x32_f16 v[54:57], v[164:167], v[232:235], v[54:57]
	v_mfma_f32_16x16x32_f16 v[38:41], v[208:211], v[232:235], v[38:41]
	v_mfma_f32_16x16x32_f16 v[46:49], v[164:167], v[240:243], v[46:49]
	v_mfma_f32_16x16x32_f16 v[34:37], v[208:211], v[240:243], v[34:37]
	v_mfma_f32_16x16x32_f16 v[62:65], v[180:183], v[220:223], v[62:65]
	v_mfma_f32_16x16x32_f16 v[50:53], v[212:215], v[220:223], v[50:53]
	v_mfma_f32_16x16x32_f16 v[58:61], v[180:183], v[228:231], v[58:61]
	v_mfma_f32_16x16x32_f16 v[42:45], v[212:215], v[228:231], v[42:45]
	v_mfma_f32_16x16x32_f16 v[54:57], v[180:183], v[236:239], v[54:57]
	v_mfma_f32_16x16x32_f16 v[38:41], v[212:215], v[236:239], v[38:41]
	v_mfma_f32_16x16x32_f16 v[46:49], v[180:183], v[244:247], v[46:49]
	v_mfma_f32_16x16x32_f16 v[34:37], v[212:215], v[244:247], v[34:37]
	s_setprio 0
	s_barrier
	s_add_i32 s19, s19, s59
	v_lshl_add_u64 v[168:169], s[2:3], 0, v[144:145]
	s_mov_b32 m0, s19
	ds_read_b128 v[216:219], v194 offset:16384
	ds_read_b128 v[220:223], v194 offset:17408
	ds_read_b128 v[224:227], v194 offset:18432
	ds_read_b128 v[228:231], v194 offset:19456
	ds_read_b128 v[232:235], v194 offset:20480
	ds_read_b128 v[236:239], v194 offset:21504
	ds_read_b128 v[240:243], v194 offset:22528
	ds_read_b128 v[244:247], v194 offset:23552
	global_load_lds_dwordx4 v[168:169], off
	s_add_i32 m0, s19, 0x2000
	s_add_u32 s20, s2, 0x40000
	v_lshl_add_u64 v[184:185], s[2:3], 0, v[148:149]
	s_addc_u32 s21, s3, 0
	s_add_i32 s19, s33, s59
	global_load_lds_dwordx4 v[184:185], off
	v_lshl_add_u64 v[196:197], s[20:21], 0, v[144:145]
	s_mov_b32 m0, s19
	v_lshl_add_u64 v[248:249], s[12:13], 0, v[146:147]
	global_load_lds_dwordx4 v[196:197], off
	v_lshl_add_u64 v[196:197], s[20:21], 0, v[148:149]
	s_add_i32 m0, s19, 0x2000
	s_nop 0
	global_load_lds_dwordx4 v[196:197], off
	v_lshl_add_u64 v[196:197], s[12:13], 0, v[142:143]
	s_mov_b32 m0, s60
	s_nop 0
	global_load_lds_dwordx4 v[196:197], off
	s_mov_b32 m0, s61
	s_nop 0
	global_load_lds_dwordx4 v[248:249], off
	s_waitcnt vmcnt(8)
	s_waitcnt lgkmcnt(0)
	s_barrier
; #define PG8_STAGE(bufoff, gbase, voff) do { _Pragma("unroll") for (int _i = 0; _i < 2; ++_i) \
;         __builtin_amdgcn_global_load_lds((const unsigned*)((const char*)(gbase) + (voff)[_i]), (PG8_LAS unsigned*)(lds + (bufoff) + ldsw + _i * 8192), 16, 0, 0); } while (0)
; #define PG8_LDA(dst, b, h) do { _Pragma("unroll") for (int m = 0; m < 4; ++m) _Pragma("unroll") for (int k = 0; k < 2; ++k) dst[m][k] = *(const PG8_LAS half8*)(lds + PG8_SA(b, h) + aoff + m * 2048 + k * 1024); } while (0)
; #define PG8_LDB(dst, b, h) do { _Pragma("unroll") for (int n = 0; n < 2; ++n) _Pragma("unroll") for (int k = 0; k < 2; ++k) dst[n][k] = *(const PG8_LAS half8*)(lds + PG8_SB(b, h) + boff + n * 2048 + k * 1024); } while (0)
; #define PG8_MMA(ai, bj, At, Bt) do { __builtin_amdgcn_s_setprio(1); _Pragma("unroll") for (int m = 0; m < 4; ++m) _Pragma("unroll") for (int n = 0; n < 2; ++n) _Pragma("unroll") for (int k = 0; k < 2; ++k) \
;         acc[ai][bj][m][n] = __builtin_amdgcn_mfma_f32_16x16x32_f16(Bt[n][k], At[m][k], acc[ai][bj][m][n], 0, 0, 0); __builtin_amdgcn_s_setprio(0); } while (0)
; #define PG8_WAIT_V(n) asm volatile("s_waitcnt vmcnt(" #n ")" ::: "memory")
; #define PG8_WAIT_L(n) asm volatile("s_waitcnt lgkmcnt(" #n ")" ::: "memory")
; #define PG8_BAR __builtin_amdgcn_s_barrier()
; #define PG8_SCHED __builtin_amdgcn_sched_barrier(0)
; template <class Epi>
; __device__ __forceinline__ void gemm_phase(PG8_LAS unsigned char* lds, const Gemm g, const StaticOrder& S_, const Epi& E) {
;     ...
;             PG8_WAIT_V(8); PG8_WAIT_L(0); PG8_BAR; PG8_MMA(1, 0, At, B0); PG8_MMA(1, 1, At, B1); PG8_BAR; PG8_SCHED;
;             PG8_LDB(B0, 1, 0); PG8_LDB(B1, 1, 1); PG8_SCHED; PG8_LDA(At, 1, 0); PG8_STAGE(PG8_SA(0, 1), a2 + hstepA, voffA);
;             PG8_WAIT_V(8); PG8_WAIT_L(0); PG8_BAR; PG8_MMA(0, 0, At, B0); PG8_MMA(0, 1, At, B1); PG8_BAR; PG8_SCHED;
	s_setprio 1
	s_waitcnt lgkmcnt(0)
	v_mfma_f32_16x16x32_f16 v[94:97], v[130:133], v[216:219], v[94:97]
	v_mfma_f32_16x16x32_f16 v[82:85], v[138:141], v[216:219], v[82:85]
	v_mfma_f32_16x16x32_f16 v[90:93], v[130:133], v[224:227], v[90:93]
	v_mfma_f32_16x16x32_f16 v[74:77], v[138:141], v[224:227], v[74:77]
	v_mfma_f32_16x16x32_f16 v[86:89], v[130:133], v[232:235], v[86:89]
	v_mfma_f32_16x16x32_f16 v[70:73], v[138:141], v[232:235], v[70:73]
	v_mfma_f32_16x16x32_f16 v[78:81], v[130:133], v[240:243], v[78:81]
	v_mfma_f32_16x16x32_f16 v[66:69], v[138:141], v[240:243], v[66:69]
	v_mfma_f32_16x16x32_f16 v[94:97], v[134:137], v[220:223], v[94:97]
	v_mfma_f32_16x16x32_f16 v[82:85], v[160:163], v[220:223], v[82:85]
	v_mfma_f32_16x16x32_f16 v[90:93], v[134:137], v[228:231], v[90:93]
	v_mfma_f32_16x16x32_f16 v[74:77], v[160:163], v[228:231], v[74:77]
	v_mfma_f32_16x16x32_f16 v[86:89], v[134:137], v[236:239], v[86:89]
	v_mfma_f32_16x16x32_f16 v[70:73], v[160:163], v[236:239], v[70:73]
	v_mfma_f32_16x16x32_f16 v[78:81], v[134:137], v[244:247], v[78:81]
	v_mfma_f32_16x16x32_f16 v[66:69], v[160:163], v[244:247], v[66:69]
	s_setprio 0
	s_setprio 1
	v_mfma_f32_16x16x32_f16 v[30:33], v[164:167], v[216:219], v[30:33]
	v_mfma_f32_16x16x32_f16 v[18:21], v[208:211], v[216:219], v[18:21]
	v_mfma_f32_16x16x32_f16 v[26:29], v[164:167], v[224:227], v[26:29]
	v_mfma_f32_16x16x32_f16 v[10:13], v[208:211], v[224:227], v[10:13]
	v_mfma_f32_16x16x32_f16 v[22:25], v[164:167], v[232:235], v[22:25]
	v_mfma_f32_16x16x32_f16 v[6:9], v[208:211], v[232:235], v[6:9]
	v_mfma_f32_16x16x32_f16 v[14:17], v[164:167], v[240:243], v[14:17]
	v_mfma_f32_16x16x32_f16 v[2:5], v[208:211], v[240:243], v[2:5]
	v_mfma_f32_16x16x32_f16 v[30:33], v[180:183], v[220:223], v[30:33]
	v_mfma_f32_16x16x32_f16 v[18:21], v[212:215], v[220:223], v[18:21]
	v_mfma_f32_16x16x32_f16 v[26:29], v[180:183], v[228:231], v[26:29]
	v_mfma_f32_16x16x32_f16 v[10:13], v[212:215], v[228:231], v[10:13]
	v_mfma_f32_16x16x32_f16 v[22:25], v[180:183], v[236:239], v[22:25]
	v_mfma_f32_16x16x32_f16 v[6:9], v[212:215], v[236:239], v[6:9]
	v_mfma_f32_16x16x32_f16 v[14:17], v[180:183], v[244:247], v[14:17]
	v_mfma_f32_16x16x32_f16 v[2:5], v[212:215], v[244:247], v[2:5]
	s_setprio 0
	s_barrier
	s_add_i32 s19, 0, 0x18000
	v_add_u32_e32 v0, s19, v187
	s_add_i32 s20, 0, 0x1c000
	ds_read_b128 v[130:133], v0
	ds_read_b128 v[134:137], v0 offset:1024
	ds_read_b128 v[138:141], v0 offset:2048
	ds_read_b128 v[160:163], v0 offset:3072
	v_add_u32_e32 v0, s20, v187
	ds_read_b128 v[164:167], v0
	ds_read_b128 v[180:183], v0 offset:1024
	ds_read_b128 v[208:211], v0 offset:2048
	ds_read_b128 v[212:215], v0 offset:3072
	s_add_u32 s12, s12, 0x40000
	s_addc_u32 s13, s13, 0
	s_mov_b32 m0, s62
	v_lshl_add_u64 v[250:251], s[12:13], 0, v[142:143]
	ds_read_b128 v[216:219], v194 offset:32768
	ds_read_b128 v[220:223], v194 offset:33792
	ds_read_b128 v[224:227], v194 offset:34816
	ds_read_b128 v[228:231], v194 offset:35840
	ds_read_b128 v[232:235], v194 offset:36864
	ds_read_b128 v[236:239], v194 offset:37888
	ds_read_b128 v[240:243], v194 offset:38912
	ds_read_b128 v[244:247], v194 offset:39936
	global_load_lds_dwordx4 v[250:251], off
	v_lshl_add_u64 v[250:251], s[12:13], 0, v[146:147]
	s_mov_b32 m0, s63
	s_nop 0
	global_load_lds_dwordx4 v[250:251], off
	s_waitcnt vmcnt(8)
	s_waitcnt lgkmcnt(0)
	s_barrier
	s_setprio 1
	s_waitcnt lgkmcnt(0)
	v_mfma_f32_16x16x32_f16 v[126:129], v[130:133], v[216:219], v[126:129]
	v_mfma_f32_16x16x32_f16 v[114:117], v[138:141], v[216:219], v[114:117]
	v_mfma_f32_16x16x32_f16 v[122:125], v[130:133], v[224:227], v[122:125]
	v_mfma_f32_16x16x32_f16 v[106:109], v[138:141], v[224:227], v[106:109]
	v_mfma_f32_16x16x32_f16 v[118:121], v[130:133], v[232:235], v[118:121]
	v_mfma_f32_16x16x32_f16 v[102:105], v[138:141], v[232:235], v[102:105]
	v_mfma_f32_16x16x32_f16 v[110:113], v[130:133], v[240:243], v[110:113]
	v_mfma_f32_16x16x32_f16 v[98:101], v[138:141], v[240:243], v[98:101]
	v_mfma_f32_16x16x32_f16 v[126:129], v[134:137], v[220:223], v[126:129]
	v_mfma_f32_16x16x32_f16 v[114:117], v[160:163], v[220:223], v[114:117]
	v_mfma_f32_16x16x32_f16 v[122:125], v[134:137], v[228:231], v[122:125]
	v_mfma_f32_16x16x32_f16 v[106:109], v[160:163], v[228:231], v[106:109]
	v_mfma_f32_16x16x32_f16 v[118:121], v[134:137], v[236:239], v[118:121]
	v_mfma_f32_16x16x32_f16 v[102:105], v[160:163], v[236:239], v[102:105]
	v_mfma_f32_16x16x32_f16 v[110:113], v[134:137], v[244:247], v[110:113]
	v_mfma_f32_16x16x32_f16 v[98:101], v[160:163], v[244:247], v[98:101]
	s_setprio 0
	s_setprio 1
	v_mfma_f32_16x16x32_f16 v[62:65], v[164:167], v[216:219], v[62:65]
	v_mfma_f32_16x16x32_f16 v[50:53], v[208:211], v[216:219], v[50:53]
	v_mfma_f32_16x16x32_f16 v[58:61], v[164:167], v[224:227], v[58:61]
	v_mfma_f32_16x16x32_f16 v[42:45], v[208:211], v[224:227], v[42:45]
	v_mfma_f32_16x16x32_f16 v[54:57], v[164:167], v[232:235], v[54:57]
	v_mfma_f32_16x16x32_f16 v[38:41], v[208:211], v[232:235], v[38:41]
	v_mfma_f32_16x16x32_f16 v[46:49], v[164:167], v[240:243], v[46:49]
	v_mfma_f32_16x16x32_f16 v[34:37], v[208:211], v[240:243], v[34:37]
	v_mfma_f32_16x16x32_f16 v[62:65], v[180:183], v[220:223], v[62:65]
	v_mfma_f32_16x16x32_f16 v[50:53], v[212:215], v[220:223], v[50:53]
	v_mfma_f32_16x16x32_f16 v[58:61], v[180:183], v[228:231], v[58:61]
	v_mfma_f32_16x16x32_f16 v[42:45], v[212:215], v[228:231], v[42:45]
	v_mfma_f32_16x16x32_f16 v[54:57], v[180:183], v[236:239], v[54:57]
	v_mfma_f32_16x16x32_f16 v[38:41], v[212:215], v[236:239], v[38:41]
	v_mfma_f32_16x16x32_f16 v[46:49], v[180:183], v[244:247], v[46:49]
	v_mfma_f32_16x16x32_f16 v[34:37], v[212:215], v[244:247], v[34:37]
	s_setprio 0
	s_barrier
; #define PG8_STAGE(bufoff, gbase, voff) do { _Pragma("unroll") for (int _i = 0; _i < 2; ++_i) \
;         __builtin_amdgcn_global_load_lds((const unsigned*)((const char*)(gbase) + (voff)[_i]), (PG8_LAS unsigned*)(lds + (bufoff) + ldsw + _i * 8192), 16, 0, 0); } while (0)
; #define PG8_LDA(dst, b, h) do { _Pragma("unroll") for (int m = 0; m < 4; ++m) _Pragma("unroll") for (int k = 0; k < 2; ++k) dst[m][k] = *(const PG8_LAS half8*)(lds + PG8_SA(b, h) + aoff + m * 2048 + k * 1024); } while (0)
; #define PG8_MMA(ai, bj, At, Bt) do { __builtin_amdgcn_s_setprio(1); _Pragma("unroll") for (int m = 0; m < 4; ++m) _Pragma("unroll") for (int n = 0; n < 2; ++n) _Pragma("unroll") for (int k = 0; k < 2; ++k) \
;         acc[ai][bj][m][n] = __builtin_amdgcn_mfma_f32_16x16x32_f16(Bt[n][k], At[m][k], acc[ai][bj][m][n], 0, 0, 0); __builtin_amdgcn_s_setprio(0); } while (0)
; #define PG8_WAIT_V(n) asm volatile("s_waitcnt vmcnt(" #n ")" ::: "memory")
; #define PG8_WAIT_L(n) asm volatile("s_waitcnt lgkmcnt(" #n ")" ::: "memory")
; #define PG8_BAR __builtin_amdgcn_s_barrier()
; #define PG8_SCHED __builtin_amdgcn_sched_barrier(0)
; template <class Epi>
; __device__ __forceinline__ void gemm_phase(PG8_LAS unsigned char* lds, const Gemm g, const StaticOrder& S_, const Epi& E) {
;     ...
;             PG8_LDA(At, 1, 1); PG8_STAGE(PG8_SB(1, 0), b3, voffB); PG8_STAGE(PG8_SB(1, 1), b3 + hstepB, voffB); PG8_STAGE(PG8_SA(1, 0), a3, voffA);
;             PG8_WAIT_V(8); PG8_WAIT_L(0); PG8_BAR; PG8_MMA(1, 0, At, B0); PG8_MMA(1, 1, At, B1); PG8_BAR; PG8_SCHED;
;         }
	s_add_i32 s12, s19, s59
	v_lshl_add_u64 v[168:169], v[168:169], 0, s[86:87]
	s_mov_b32 m0, s12
	ds_read_b128 v[216:219], v194 offset:49152
	ds_read_b128 v[220:223], v194 offset:50176
	ds_read_b128 v[224:227], v194 offset:51200
	ds_read_b128 v[228:231], v194 offset:52224
	ds_read_b128 v[232:235], v194 offset:53248
	ds_read_b128 v[236:239], v194 offset:54272
	ds_read_b128 v[240:243], v194 offset:55296
	ds_read_b128 v[244:247], v194 offset:56320
	global_load_lds_dwordx4 v[168:169], off
	s_add_i32 m0, s12, 0x2000
	s_add_u32 s2, s2, 0x40080
	v_lshl_add_u64 v[168:169], v[184:185], 0, s[86:87]
	s_addc_u32 s3, s3, 0
	s_add_i32 s12, s20, s59
	global_load_lds_dwordx4 v[168:169], off
	v_lshl_add_u64 v[168:169], s[2:3], 0, v[144:145]
	s_mov_b32 m0, s12
	s_nop 0
	global_load_lds_dwordx4 v[168:169], off
	v_lshl_add_u64 v[168:169], s[2:3], 0, v[148:149]
	s_add_i32 m0, s12, 0x2000
	s_nop 0
	global_load_lds_dwordx4 v[168:169], off
	v_lshl_add_u64 v[168:169], v[196:197], 0, s[86:87]
	s_mov_b32 m0, s67
	s_nop 0
	global_load_lds_dwordx4 v[168:169], off
	v_lshl_add_u64 v[168:169], v[248:249], 0, s[86:87]
	s_mov_b32 m0, s68
	s_nop 0
	global_load_lds_dwordx4 v[168:169], off
	s_waitcnt vmcnt(8)
	s_waitcnt lgkmcnt(0)
	s_barrier
	s_setprio 1
	s_waitcnt lgkmcnt(0)
	v_mfma_f32_16x16x32_f16 v[94:97], v[130:133], v[216:219], v[94:97]
	v_mfma_f32_16x16x32_f16 v[82:85], v[138:141], v[216:219], v[82:85]
	v_mfma_f32_16x16x32_f16 v[90:93], v[130:133], v[224:227], v[90:93]
	v_mfma_f32_16x16x32_f16 v[74:77], v[138:141], v[224:227], v[74:77]
	v_mfma_f32_16x16x32_f16 v[86:89], v[130:133], v[232:235], v[86:89]
	v_mfma_f32_16x16x32_f16 v[70:73], v[138:141], v[232:235], v[70:73]
	v_mfma_f32_16x16x32_f16 v[78:81], v[130:133], v[240:243], v[78:81]
	v_mfma_f32_16x16x32_f16 v[66:69], v[138:141], v[240:243], v[66:69]
	v_mfma_f32_16x16x32_f16 v[94:97], v[134:137], v[220:223], v[94:97]
	v_mfma_f32_16x16x32_f16 v[82:85], v[160:163], v[220:223], v[82:85]
	v_mfma_f32_16x16x32_f16 v[90:93], v[134:137], v[228:231], v[90:93]
	v_mfma_f32_16x16x32_f16 v[74:77], v[160:163], v[228:231], v[74:77]
	v_mfma_f32_16x16x32_f16 v[86:89], v[134:137], v[236:239], v[86:89]
	v_mfma_f32_16x16x32_f16 v[70:73], v[160:163], v[236:239], v[70:73]
	v_mfma_f32_16x16x32_f16 v[78:81], v[134:137], v[244:247], v[78:81]
	v_mfma_f32_16x16x32_f16 v[66:69], v[160:163], v[244:247], v[66:69]
	s_setprio 0
	s_setprio 1
	v_mfma_f32_16x16x32_f16 v[30:33], v[164:167], v[216:219], v[30:33]
	v_mfma_f32_16x16x32_f16 v[18:21], v[208:211], v[216:219], v[18:21]
	v_mfma_f32_16x16x32_f16 v[26:29], v[164:167], v[224:227], v[26:29]
	v_mfma_f32_16x16x32_f16 v[10:13], v[208:211], v[224:227], v[10:13]
	v_mfma_f32_16x16x32_f16 v[22:25], v[164:167], v[232:235], v[22:25]
	v_mfma_f32_16x16x32_f16 v[6:9], v[208:211], v[232:235], v[6:9]
	v_mfma_f32_16x16x32_f16 v[14:17], v[164:167], v[240:243], v[14:17]
	v_mfma_f32_16x16x32_f16 v[2:5], v[208:211], v[240:243], v[2:5]
	v_mfma_f32_16x16x32_f16 v[30:33], v[180:183], v[220:223], v[30:33]
	v_mfma_f32_16x16x32_f16 v[18:21], v[212:215], v[220:223], v[18:21]
	v_mfma_f32_16x16x32_f16 v[26:29], v[180:183], v[228:231], v[26:29]
	v_mfma_f32_16x16x32_f16 v[10:13], v[212:215], v[228:231], v[10:13]
	v_mfma_f32_16x16x32_f16 v[22:25], v[180:183], v[236:239], v[22:25]
	v_mfma_f32_16x16x32_f16 v[6:9], v[212:215], v[236:239], v[6:9]
	v_mfma_f32_16x16x32_f16 v[14:17], v[180:183], v[244:247], v[14:17]
	v_mfma_f32_16x16x32_f16 v[2:5], v[212:215], v[244:247], v[2:5]
	s_setprio 0
	s_add_i32 s18, s18, 2
	s_add_u32 s16, s16, 0x100
	s_addc_u32 s17, s17, 0
	s_add_u32 s10, s10, 0x100
	s_addc_u32 s11, s11, 0
	s_cmp_gt_u32 s18, 13
	s_barrier
	s_cbranch_scc0 .LBB0_183
	s_and_b64 vcc, exec, s[30:31]
	s_cbranch_vccz .LBB0_186
	s_barrier

; #define PG8_STAGE(bufoff, gbase, voff) do { _Pragma("unroll") for (int _i = 0; _i < 2; ++_i) \
;         __builtin_amdgcn_global_load_lds((const unsigned*)((const char*)(gbase) + (voff)[_i]), (PG8_LAS unsigned*)(lds + (bufoff) + ldsw + _i * 8192), 16, 0, 0); } while (0)
; #define PG8_LDA(dst, b, h) do { _Pragma("unroll") for (int m = 0; m < 4; ++m) _Pragma("unroll") for (int k = 0; k < 2; ++k) dst[m][k] = *(const PG8_LAS half8*)(lds + PG8_SA(b, h) + aoff + m * 2048 + k * 1024); } while (0)
; #define PG8_LDB(dst, b, h) do { _Pragma("unroll") for (int n = 0; n < 2; ++n) _Pragma("unroll") for (int k = 0; k < 2; ++k) dst[n][k] = *(const PG8_LAS half8*)(lds + PG8_SB(b, h) + boff + n * 2048 + k * 1024); } while (0)
; #define PG8_MMA(ai, bj, At, Bt) do { __builtin_amdgcn_s_setprio(1); _Pragma("unroll") for (int m = 0; m < 4; ++m) _Pragma("unroll") for (int n = 0; n < 2; ++n) _Pragma("unroll") for (int k = 0; k < 2; ++k) \
;         acc[ai][bj][m][n] = __builtin_amdgcn_mfma_f32_16x16x32_f16(Bt[n][k], At[m][k], acc[ai][bj][m][n], 0, 0, 0); __builtin_amdgcn_s_setprio(0); } while (0)
; #define PG8_WAIT_V(n) asm volatile("s_waitcnt vmcnt(" #n ")" ::: "memory")
; #define PG8_WAIT_L(n) asm volatile("s_waitcnt lgkmcnt(" #n ")" ::: "memory")
; #define PG8_BAR __builtin_amdgcn_s_barrier()
; #define PG8_SCHED __builtin_amdgcn_sched_barrier(0)
; template <class Epi>
; __device__ __forceinline__ void gemm_phase(PG8_LAS unsigned char* lds, const Gemm g, const StaticOrder& S_, const Epi& E) {
;     ...
;             const bool last = (t == nt - 2);
;             const char* a1 = cA + (size_t)(t + 1) * kstep;
;             const char* a2 = last ? nA : cA + (size_t)(t + 2) * kstep; const char* b2 = last ? nB : cB + (size_t)(t + 2) * kstep;
;             const char* a3 = a2 + kstep; const char* b3 = b2 + kstep;
;             PG8_LDB(B0, 0, 0); PG8_LDB(B1, 0, 1); PG8_SCHED; PG8_LDA(At, 0, 0); PG8_STAGE(PG8_SA(1, 1), a1 + hstepA, voffA);
;             PG8_WAIT_V(8); PG8_WAIT_L(0); PG8_BAR; PG8_MMA(0, 0, At, B0); PG8_MMA(0, 1, At, B1); PG8_BAR; PG8_SCHED;
;             PG8_LDA(At, 0, 1); PG8_STAGE(PG8_SB(0, 0), b2, voffB); PG8_STAGE(PG8_SB(0, 1), b2 + hstepB, voffB); PG8_STAGE(PG8_SA(0, 0), a2, voffA);
;             PG8_WAIT_V(8); PG8_WAIT_L(0); PG8_BAR; PG8_MMA(1, 0, At, B0); PG8_MMA(1, 1, At, B1); PG8_BAR; PG8_SCHED;
.LBB0_1168:
	s_add_u32 s2, s20, 0xfffc0080
	s_addc_u32 s3, s21, -1
	s_add_i32 s33, 0, 0x10000
	s_cmp_eq_u32 s44, 12
	s_cselect_b32 s23, s15, s3
	s_cselect_b32 s22, s40, s2
	s_cselect_b32 s3, s13, s43
	s_cselect_b32 s2, s41, s42
	s_add_i32 s45, 0, 0x14000
	v_add_u32_e32 v156, s33, v141
	v_add_u32_e32 v168, s45, v141
	ds_read_b128 v[144:147], v156
	ds_read_b128 v[148:151], v156 offset:1024
	ds_read_b128 v[152:155], v156 offset:2048
	ds_read_b128 v[156:159], v156 offset:3072
	ds_read_b128 v[160:163], v168
	ds_read_b128 v[164:167], v168 offset:1024
	ds_read_b128 v[180:183], v168 offset:2048
	ds_read_b128 v[184:187], v168 offset:3072
	v_lshl_add_u64 v[168:169], s[20:21], 0, v[138:139]
	s_add_i32 m0, s11, 0xc000
	ds_read_b128 v[188:191], v143
	ds_read_b128 v[192:195], v143 offset:1024
	ds_read_b128 v[208:211], v143 offset:2048
	ds_read_b128 v[212:215], v143 offset:3072
	ds_read_b128 v[216:219], v143 offset:4096
	ds_read_b128 v[220:223], v143 offset:5120
	ds_read_b128 v[224:227], v143 offset:6144
	ds_read_b128 v[228:231], v143 offset:7168
	global_load_lds_dwordx4 v[168:169], off
	v_lshl_add_u64 v[168:169], s[20:21], 0, v[136:137]
	s_add_i32 m0, s11, 0xe000
	s_nop 0
	global_load_lds_dwordx4 v[168:169], off
	s_waitcnt vmcnt(8)
	s_waitcnt lgkmcnt(0)
	s_barrier
	s_setprio 1
	s_waitcnt lgkmcnt(0)
	v_mfma_f32_16x16x32_f16 v[126:129], v[144:147], v[188:191], v[126:129]
	v_mfma_f32_16x16x32_f16 v[122:125], v[152:155], v[188:191], v[122:125]
	v_mfma_f32_16x16x32_f16 v[118:121], v[144:147], v[208:211], v[118:121]
	v_mfma_f32_16x16x32_f16 v[114:117], v[152:155], v[208:211], v[114:117]
	v_mfma_f32_16x16x32_f16 v[102:105], v[144:147], v[216:219], v[102:105]
	v_mfma_f32_16x16x32_f16 v[98:101], v[152:155], v[216:219], v[98:101]
	v_mfma_f32_16x16x32_f16 v[86:89], v[144:147], v[224:227], v[86:89]
	v_mfma_f32_16x16x32_f16 v[82:85], v[152:155], v[224:227], v[82:85]
	v_mfma_f32_16x16x32_f16 v[126:129], v[148:151], v[192:195], v[126:129]
	v_mfma_f32_16x16x32_f16 v[122:125], v[156:159], v[192:195], v[122:125]
	v_mfma_f32_16x16x32_f16 v[118:121], v[148:151], v[212:215], v[118:121]
	v_mfma_f32_16x16x32_f16 v[114:117], v[156:159], v[212:215], v[114:117]
	v_mfma_f32_16x16x32_f16 v[102:105], v[148:151], v[220:223], v[102:105]
	v_mfma_f32_16x16x32_f16 v[98:101], v[156:159], v[220:223], v[98:101]
	v_mfma_f32_16x16x32_f16 v[86:89], v[148:151], v[228:231], v[86:89]
	v_mfma_f32_16x16x32_f16 v[82:85], v[156:159], v[228:231], v[82:85]
	s_setprio 0
	s_setprio 1
	v_mfma_f32_16x16x32_f16 v[110:113], v[160:163], v[188:191], v[110:113]
	v_mfma_f32_16x16x32_f16 v[106:109], v[180:183], v[188:191], v[106:109]
	v_mfma_f32_16x16x32_f16 v[94:97], v[160:163], v[208:211], v[94:97]
	v_mfma_f32_16x16x32_f16 v[90:93], v[180:183], v[208:211], v[90:93]
	v_mfma_f32_16x16x32_f16 v[78:81], v[160:163], v[216:219], v[78:81]
	v_mfma_f32_16x16x32_f16 v[74:77], v[180:183], v[216:219], v[74:77]
	v_mfma_f32_16x16x32_f16 v[70:73], v[160:163], v[224:227], v[70:73]
	v_mfma_f32_16x16x32_f16 v[66:69], v[180:183], v[224:227], v[66:69]
	v_mfma_f32_16x16x32_f16 v[110:113], v[164:167], v[192:195], v[110:113]
	v_mfma_f32_16x16x32_f16 v[106:109], v[184:187], v[192:195], v[106:109]
	v_mfma_f32_16x16x32_f16 v[94:97], v[164:167], v[212:215], v[94:97]
	v_mfma_f32_16x16x32_f16 v[90:93], v[184:187], v[212:215], v[90:93]
	v_mfma_f32_16x16x32_f16 v[78:81], v[164:167], v[220:223], v[78:81]
	v_mfma_f32_16x16x32_f16 v[74:77], v[184:187], v[220:223], v[74:77]
	v_mfma_f32_16x16x32_f16 v[70:73], v[164:167], v[228:231], v[70:73]
	v_mfma_f32_16x16x32_f16 v[66:69], v[184:187], v[228:231], v[66:69]
	s_setprio 0
	s_barrier
	s_add_i32 s33, s33, s30
	v_lshl_add_u64 v[168:169], s[2:3], 0, v[0:1]
	s_mov_b32 m0, s33
	ds_read_b128 v[188:191], v143 offset:16384
	ds_read_b128 v[192:195], v143 offset:17408
	ds_read_b128 v[208:211], v143 offset:18432
	ds_read_b128 v[212:215], v143 offset:19456
	ds_read_b128 v[216:219], v143 offset:20480
	ds_read_b128 v[220:223], v143 offset:21504
	ds_read_b128 v[224:227], v143 offset:22528
	ds_read_b128 v[228:231], v143 offset:23552
	global_load_lds_dwordx4 v[168:169], off
	s_add_i32 m0, s33, 0x2000
	s_add_u32 s46, s2, 0x40000
	v_lshl_add_u64 v[196:197], s[2:3], 0, v[134:135]
	s_addc_u32 s47, s3, 0
	s_add_i32 s33, s45, s30
	global_load_lds_dwordx4 v[196:197], off
	v_lshl_add_u64 v[232:233], s[46:47], 0, v[0:1]
	s_mov_b32 m0, s33
	v_lshl_add_u64 v[234:235], s[22:23], 0, v[132:133]
	global_load_lds_dwordx4 v[232:233], off
	v_lshl_add_u64 v[232:233], s[46:47], 0, v[134:135]
	s_add_i32 m0, s33, 0x2000
	s_nop 0
	global_load_lds_dwordx4 v[232:233], off
	v_lshl_add_u64 v[232:233], s[22:23], 0, v[130:131]
	s_mov_b32 m0, s11
	s_nop 0
	global_load_lds_dwordx4 v[232:233], off
	s_mov_b32 m0, s31
	s_nop 0
	global_load_lds_dwordx4 v[234:235], off
	s_waitcnt vmcnt(8)
	s_waitcnt lgkmcnt(0)
	s_barrier
; #define PG8_STAGE(bufoff, gbase, voff) do { _Pragma("unroll") for (int _i = 0; _i < 2; ++_i) \
;         __builtin_amdgcn_global_load_lds((const unsigned*)((const char*)(gbase) + (voff)[_i]), (PG8_LAS unsigned*)(lds + (bufoff) + ldsw + _i * 8192), 16, 0, 0); } while (0)
; #define PG8_LDA(dst, b, h) do { _Pragma("unroll") for (int m = 0; m < 4; ++m) _Pragma("unroll") for (int k = 0; k < 2; ++k) dst[m][k] = *(const PG8_LAS half8*)(lds + PG8_SA(b, h) + aoff + m * 2048 + k * 1024); } while (0)
; #define PG8_LDB(dst, b, h) do { _Pragma("unroll") for (int n = 0; n < 2; ++n) _Pragma("unroll") for (int k = 0; k < 2; ++k) dst[n][k] = *(const PG8_LAS half8*)(lds + PG8_SB(b, h) + boff + n * 2048 + k * 1024); } while (0)
; #define PG8_MMA(ai, bj, At, Bt) do { __builtin_amdgcn_s_setprio(1); _Pragma("unroll") for (int m = 0; m < 4; ++m) _Pragma("unroll") for (int n = 0; n < 2; ++n) _Pragma("unroll") for (int k = 0; k < 2; ++k) \
;         acc[ai][bj][m][n] = __builtin_amdgcn_mfma_f32_16x16x32_f16(Bt[n][k], At[m][k], acc[ai][bj][m][n], 0, 0, 0); __builtin_amdgcn_s_setprio(0); } while (0)
; #define PG8_WAIT_V(n) asm volatile("s_waitcnt vmcnt(" #n ")" ::: "memory")
; #define PG8_WAIT_L(n) asm volatile("s_waitcnt lgkmcnt(" #n ")" ::: "memory")
; #define PG8_BAR __builtin_amdgcn_s_barrier()
; #define PG8_SCHED __builtin_amdgcn_sched_barrier(0)
; template <class Epi>
; __device__ __forceinline__ void gemm_phase(PG8_LAS unsigned char* lds, const Gemm g, const StaticOrder& S_, const Epi& E) {
;     ...
;             PG8_WAIT_V(8); PG8_WAIT_L(0); PG8_BAR; PG8_MMA(1, 0, At, B0); PG8_MMA(1, 1, At, B1); PG8_BAR; PG8_SCHED;
;             PG8_LDB(B0, 1, 0); PG8_LDB(B1, 1, 1); PG8_SCHED; PG8_LDA(At, 1, 0); PG8_STAGE(PG8_SA(0, 1), a2 + hstepA, voffA);
;             PG8_WAIT_V(8); PG8_WAIT_L(0); PG8_BAR; PG8_MMA(0, 0, At, B0); PG8_MMA(0, 1, At, B1); PG8_BAR; PG8_SCHED;
;             PG8_LDA(At, 1, 1); PG8_STAGE(PG8_SB(1, 0), b3, voffB); PG8_STAGE(PG8_SB(1, 1), b3 + hstepB, voffB); PG8_STAGE(PG8_SA(1, 0), a3, voffA);
;             PG8_WAIT_V(8); PG8_WAIT_L(0); PG8_BAR; PG8_MMA(1, 0, At, B0); PG8_MMA(1, 1, At, B1); PG8_BAR; PG8_SCHED;
	s_setprio 1
	s_waitcnt lgkmcnt(0)
	v_mfma_f32_16x16x32_f16 v[62:65], v[144:147], v[188:191], v[62:65]
	v_mfma_f32_16x16x32_f16 v[58:61], v[152:155], v[188:191], v[58:61]
	v_mfma_f32_16x16x32_f16 v[54:57], v[144:147], v[208:211], v[54:57]
	v_mfma_f32_16x16x32_f16 v[50:53], v[152:155], v[208:211], v[50:53]
	v_mfma_f32_16x16x32_f16 v[38:41], v[144:147], v[216:219], v[38:41]
	v_mfma_f32_16x16x32_f16 v[34:37], v[152:155], v[216:219], v[34:37]
	v_mfma_f32_16x16x32_f16 v[22:25], v[144:147], v[224:227], v[22:25]
	v_mfma_f32_16x16x32_f16 v[18:21], v[152:155], v[224:227], v[18:21]
	v_mfma_f32_16x16x32_f16 v[62:65], v[148:151], v[192:195], v[62:65]
	v_mfma_f32_16x16x32_f16 v[58:61], v[156:159], v[192:195], v[58:61]
	v_mfma_f32_16x16x32_f16 v[54:57], v[148:151], v[212:215], v[54:57]
	v_mfma_f32_16x16x32_f16 v[50:53], v[156:159], v[212:215], v[50:53]
	v_mfma_f32_16x16x32_f16 v[38:41], v[148:151], v[220:223], v[38:41]
	v_mfma_f32_16x16x32_f16 v[34:37], v[156:159], v[220:223], v[34:37]
	v_mfma_f32_16x16x32_f16 v[22:25], v[148:151], v[228:231], v[22:25]
	v_mfma_f32_16x16x32_f16 v[18:21], v[156:159], v[228:231], v[18:21]
	s_setprio 0
	s_setprio 1
	v_mfma_f32_16x16x32_f16 v[46:49], v[160:163], v[188:191], v[46:49]
	v_mfma_f32_16x16x32_f16 v[42:45], v[180:183], v[188:191], v[42:45]
	v_mfma_f32_16x16x32_f16 v[30:33], v[160:163], v[208:211], v[30:33]
	v_mfma_f32_16x16x32_f16 v[26:29], v[180:183], v[208:211], v[26:29]
	v_mfma_f32_16x16x32_f16 v[14:17], v[160:163], v[216:219], v[14:17]
	v_mfma_f32_16x16x32_f16 v[10:13], v[180:183], v[216:219], v[10:13]
	v_mfma_f32_16x16x32_f16 v[6:9], v[160:163], v[224:227], v[6:9]
	v_mfma_f32_16x16x32_f16 v[2:5], v[180:183], v[224:227], v[2:5]
	v_mfma_f32_16x16x32_f16 v[46:49], v[164:167], v[192:195], v[46:49]
	v_mfma_f32_16x16x32_f16 v[42:45], v[184:187], v[192:195], v[42:45]
	v_mfma_f32_16x16x32_f16 v[30:33], v[164:167], v[212:215], v[30:33]
	v_mfma_f32_16x16x32_f16 v[26:29], v[184:187], v[212:215], v[26:29]
	v_mfma_f32_16x16x32_f16 v[14:17], v[164:167], v[220:223], v[14:17]
	v_mfma_f32_16x16x32_f16 v[10:13], v[184:187], v[220:223], v[10:13]
	v_mfma_f32_16x16x32_f16 v[6:9], v[164:167], v[228:231], v[6:9]
	v_mfma_f32_16x16x32_f16 v[2:5], v[184:187], v[228:231], v[2:5]
	s_setprio 0
	s_barrier
	s_add_i32 s33, 0, 0x18000
	s_add_i32 s45, 0, 0x1c000
	v_add_u32_e32 v156, s33, v141
	v_add_u32_e32 v173, s45, v141
	ds_read_b128 v[144:147], v156
	ds_read_b128 v[148:151], v156 offset:1024
	ds_read_b128 v[152:155], v156 offset:2048
	ds_read_b128 v[156:159], v156 offset:3072
	ds_read_b128 v[160:163], v173
	ds_read_b128 v[164:167], v173 offset:1024
	ds_read_b128 v[180:183], v173 offset:2048
	ds_read_b128 v[184:187], v173 offset:3072
	s_add_u32 s22, s22, 0x40000
	s_addc_u32 s23, s23, 0
	s_mov_b32 m0, s34
	v_lshl_add_u64 v[236:237], s[22:23], 0, v[130:131]
	ds_read_b128 v[188:191], v143 offset:32768
	ds_read_b128 v[192:195], v143 offset:33792
	ds_read_b128 v[208:211], v143 offset:34816
	ds_read_b128 v[212:215], v143 offset:35840
	ds_read_b128 v[216:219], v143 offset:36864
	ds_read_b128 v[220:223], v143 offset:37888
	ds_read_b128 v[224:227], v143 offset:38912
	ds_read_b128 v[228:231], v143 offset:39936
	global_load_lds_dwordx4 v[236:237], off
	v_lshl_add_u64 v[236:237], s[22:23], 0, v[132:133]
	s_mov_b32 m0, s35
	s_nop 0
	global_load_lds_dwordx4 v[236:237], off
	s_waitcnt vmcnt(8)
	s_waitcnt lgkmcnt(0)
	s_barrier
	s_setprio 1
	s_waitcnt lgkmcnt(0)
	v_mfma_f32_16x16x32_f16 v[126:129], v[144:147], v[188:191], v[126:129]
	v_mfma_f32_16x16x32_f16 v[122:125], v[152:155], v[188:191], v[122:125]
	v_mfma_f32_16x16x32_f16 v[118:121], v[144:147], v[208:211], v[118:121]
	v_mfma_f32_16x16x32_f16 v[114:117], v[152:155], v[208:211], v[114:117]
	v_mfma_f32_16x16x32_f16 v[102:105], v[144:147], v[216:219], v[102:105]
	v_mfma_f32_16x16x32_f16 v[98:101], v[152:155], v[216:219], v[98:101]
	v_mfma_f32_16x16x32_f16 v[86:89], v[144:147], v[224:227], v[86:89]
	v_mfma_f32_16x16x32_f16 v[82:85], v[152:155], v[224:227], v[82:85]
	v_mfma_f32_16x16x32_f16 v[126:129], v[148:151], v[192:195], v[126:129]
	v_mfma_f32_16x16x32_f16 v[122:125], v[156:159], v[192:195], v[122:125]
	v_mfma_f32_16x16x32_f16 v[118:121], v[148:151], v[212:215], v[118:121]
	v_mfma_f32_16x16x32_f16 v[114:117], v[156:159], v[212:215], v[114:117]
	v_mfma_f32_16x16x32_f16 v[102:105], v[148:151], v[220:223], v[102:105]
	v_mfma_f32_16x16x32_f16 v[98:101], v[156:159], v[220:223], v[98:101]
	v_mfma_f32_16x16x32_f16 v[86:89], v[148:151], v[228:231], v[86:89]
	v_mfma_f32_16x16x32_f16 v[82:85], v[156:159], v[228:231], v[82:85]
	s_setprio 0
	s_setprio 1
	v_mfma_f32_16x16x32_f16 v[110:113], v[160:163], v[188:191], v[110:113]
	v_mfma_f32_16x16x32_f16 v[106:109], v[180:183], v[188:191], v[106:109]
	v_mfma_f32_16x16x32_f16 v[94:97], v[160:163], v[208:211], v[94:97]
	v_mfma_f32_16x16x32_f16 v[90:93], v[180:183], v[208:211], v[90:93]
	v_mfma_f32_16x16x32_f16 v[78:81], v[160:163], v[216:219], v[78:81]
	v_mfma_f32_16x16x32_f16 v[74:77], v[180:183], v[216:219], v[74:77]
	v_mfma_f32_16x16x32_f16 v[70:73], v[160:163], v[224:227], v[70:73]
	v_mfma_f32_16x16x32_f16 v[66:69], v[180:183], v[224:227], v[66:69]
	v_mfma_f32_16x16x32_f16 v[110:113], v[164:167], v[192:195], v[110:113]
	v_mfma_f32_16x16x32_f16 v[106:109], v[184:187], v[192:195], v[106:109]
	v_mfma_f32_16x16x32_f16 v[94:97], v[164:167], v[212:215], v[94:97]
	v_mfma_f32_16x16x32_f16 v[90:93], v[184:187], v[212:215], v[90:93]
	v_mfma_f32_16x16x32_f16 v[78:81], v[164:167], v[220:223], v[78:81]
	v_mfma_f32_16x16x32_f16 v[74:77], v[184:187], v[220:223], v[74:77]
	v_mfma_f32_16x16x32_f16 v[70:73], v[164:167], v[228:231], v[70:73]
	v_mfma_f32_16x16x32_f16 v[66:69], v[184:187], v[228:231], v[66:69]
	s_setprio 0
	s_barrier
; #define PG8_STAGE(bufoff, gbase, voff) do { _Pragma("unroll") for (int _i = 0; _i < 2; ++_i) \
;         __builtin_amdgcn_global_load_lds((const unsigned*)((const char*)(gbase) + (voff)[_i]), (PG8_LAS unsigned*)(lds + (bufoff) + ldsw + _i * 8192), 16, 0, 0); } while (0)
; #define PG8_LDA(dst, b, h) do { _Pragma("unroll") for (int m = 0; m < 4; ++m) _Pragma("unroll") for (int k = 0; k < 2; ++k) dst[m][k] = *(const PG8_LAS half8*)(lds + PG8_SA(b, h) + aoff + m * 2048 + k * 1024); } while (0)
; #define PG8_MMA(ai, bj, At, Bt) do { __builtin_amdgcn_s_setprio(1); _Pragma("unroll") for (int m = 0; m < 4; ++m) _Pragma("unroll") for (int n = 0; n < 2; ++n) _Pragma("unroll") for (int k = 0; k < 2; ++k) \
;         acc[ai][bj][m][n] = __builtin_amdgcn_mfma_f32_16x16x32_f16(Bt[n][k], At[m][k], acc[ai][bj][m][n], 0, 0, 0); __builtin_amdgcn_s_setprio(0); } while (0)
; #define PG8_WAIT_V(n) asm volatile("s_waitcnt vmcnt(" #n ")" ::: "memory")
; #define PG8_WAIT_L(n) asm volatile("s_waitcnt lgkmcnt(" #n ")" ::: "memory")
; #define PG8_BAR __builtin_amdgcn_s_barrier()
; #define PG8_SCHED __builtin_amdgcn_sched_barrier(0)
; template <class Epi>
; __device__ __forceinline__ void gemm_phase(PG8_LAS unsigned char* lds, const Gemm g, const StaticOrder& S_, const Epi& E) {
;     ...
;             PG8_LDA(At, 1, 1); PG8_STAGE(PG8_SB(1, 0), b3, voffB); PG8_STAGE(PG8_SB(1, 1), b3 + hstepB, voffB); PG8_STAGE(PG8_SA(1, 0), a3, voffA);
;             PG8_WAIT_V(8); PG8_WAIT_L(0); PG8_BAR; PG8_MMA(1, 0, At, B0); PG8_MMA(1, 1, At, B1); PG8_BAR; PG8_SCHED;
;         }
	s_add_i32 s22, s33, s30
	v_lshl_add_u64 v[168:169], v[168:169], 0, s[86:87]
	s_mov_b32 m0, s22
	ds_read_b128 v[188:191], v143 offset:49152
	ds_read_b128 v[192:195], v143 offset:50176
	ds_read_b128 v[208:211], v143 offset:51200
	ds_read_b128 v[212:215], v143 offset:52224
	ds_read_b128 v[216:219], v143 offset:53248
	ds_read_b128 v[220:223], v143 offset:54272
	ds_read_b128 v[224:227], v143 offset:55296
	ds_read_b128 v[228:231], v143 offset:56320
	global_load_lds_dwordx4 v[168:169], off
	s_add_i32 m0, s22, 0x2000
	s_add_u32 s2, s2, 0x40080
	v_lshl_add_u64 v[168:169], v[196:197], 0, s[86:87]
	s_addc_u32 s3, s3, 0
	s_add_i32 s22, s45, s30
	global_load_lds_dwordx4 v[168:169], off
	v_lshl_add_u64 v[168:169], s[2:3], 0, v[0:1]
	s_mov_b32 m0, s22
	s_nop 0
	global_load_lds_dwordx4 v[168:169], off
	v_lshl_add_u64 v[168:169], s[2:3], 0, v[134:135]
	s_add_i32 m0, s22, 0x2000
	s_nop 0
	global_load_lds_dwordx4 v[168:169], off
	v_lshl_add_u64 v[168:169], v[232:233], 0, s[86:87]
	s_mov_b32 m0, s36
	s_nop 0
	global_load_lds_dwordx4 v[168:169], off
	v_lshl_add_u64 v[168:169], v[234:235], 0, s[86:87]
	s_mov_b32 m0, s37
	s_nop 0
	global_load_lds_dwordx4 v[168:169], off
	s_waitcnt vmcnt(8)
	s_waitcnt lgkmcnt(0)
	s_barrier
	s_setprio 1
	s_waitcnt lgkmcnt(0)
	v_mfma_f32_16x16x32_f16 v[62:65], v[144:147], v[188:191], v[62:65]
	v_mfma_f32_16x16x32_f16 v[58:61], v[152:155], v[188:191], v[58:61]
	v_mfma_f32_16x16x32_f16 v[54:57], v[144:147], v[208:211], v[54:57]
	v_mfma_f32_16x16x32_f16 v[50:53], v[152:155], v[208:211], v[50:53]
	v_mfma_f32_16x16x32_f16 v[38:41], v[144:147], v[216:219], v[38:41]
	v_mfma_f32_16x16x32_f16 v[34:37], v[152:155], v[216:219], v[34:37]
	v_mfma_f32_16x16x32_f16 v[22:25], v[144:147], v[224:227], v[22:25]
	v_mfma_f32_16x16x32_f16 v[18:21], v[152:155], v[224:227], v[18:21]
	v_mfma_f32_16x16x32_f16 v[62:65], v[148:151], v[192:195], v[62:65]
	v_mfma_f32_16x16x32_f16 v[58:61], v[156:159], v[192:195], v[58:61]
	v_mfma_f32_16x16x32_f16 v[54:57], v[148:151], v[212:215], v[54:57]
	v_mfma_f32_16x16x32_f16 v[50:53], v[156:159], v[212:215], v[50:53]
	v_mfma_f32_16x16x32_f16 v[38:41], v[148:151], v[220:223], v[38:41]
	v_mfma_f32_16x16x32_f16 v[34:37], v[156:159], v[220:223], v[34:37]
	v_mfma_f32_16x16x32_f16 v[22:25], v[148:151], v[228:231], v[22:25]
	v_mfma_f32_16x16x32_f16 v[18:21], v[156:159], v[228:231], v[18:21]
	s_setprio 0
	s_setprio 1
	v_mfma_f32_16x16x32_f16 v[46:49], v[160:163], v[188:191], v[46:49]
	v_mfma_f32_16x16x32_f16 v[42:45], v[180:183], v[188:191], v[42:45]
	v_mfma_f32_16x16x32_f16 v[30:33], v[160:163], v[208:211], v[30:33]
	v_mfma_f32_16x16x32_f16 v[26:29], v[180:183], v[208:211], v[26:29]
	v_mfma_f32_16x16x32_f16 v[14:17], v[160:163], v[216:219], v[14:17]
	v_mfma_f32_16x16x32_f16 v[10:13], v[180:183], v[216:219], v[10:13]
	v_mfma_f32_16x16x32_f16 v[6:9], v[160:163], v[224:227], v[6:9]
	v_mfma_f32_16x16x32_f16 v[2:5], v[180:183], v[224:227], v[2:5]
	v_mfma_f32_16x16x32_f16 v[46:49], v[164:167], v[192:195], v[46:49]
	v_mfma_f32_16x16x32_f16 v[42:45], v[184:187], v[192:195], v[42:45]
	v_mfma_f32_16x16x32_f16 v[30:33], v[164:167], v[212:215], v[30:33]
	v_mfma_f32_16x16x32_f16 v[26:29], v[184:187], v[212:215], v[26:29]
	v_mfma_f32_16x16x32_f16 v[14:17], v[164:167], v[220:223], v[14:17]
	v_mfma_f32_16x16x32_f16 v[10:13], v[184:187], v[220:223], v[10:13]
	v_mfma_f32_16x16x32_f16 v[6:9], v[164:167], v[228:231], v[6:9]
	v_mfma_f32_16x16x32_f16 v[2:5], v[184:187], v[228:231], v[2:5]
	s_setprio 0
	s_add_i32 s44, s44, 2
	s_add_u32 s42, s42, 0x100
	s_addc_u32 s43, s43, 0
	s_add_u32 s20, s20, 0x100
	s_addc_u32 s21, s21, 0
	s_cmp_gt_u32 s44, 13
	s_barrier
	s_cbranch_scc0 .LBB0_1168
	s_and_b64 vcc, exec, s[8:9]
	s_cbranch_vccz .LBB0_1171
	s_barrier

; #define PG8_STAGE(bufoff, gbase, voff) do { _Pragma("unroll") for (int _i = 0; _i < 2; ++_i) \
;         __builtin_amdgcn_global_load_lds((const unsigned*)((const char*)(gbase) + (voff)[_i]), (PG8_LAS unsigned*)(lds + (bufoff) + ldsw + _i * 8192), 16, 0, 0); } while (0)
; #define PG8_LDA(dst, b, h) do { _Pragma("unroll") for (int m = 0; m < 4; ++m) _Pragma("unroll") for (int k = 0; k < 2; ++k) dst[m][k] = *(const PG8_LAS half8*)(lds + PG8_SA(b, h) + aoff + m * 2048 + k * 1024); } while (0)
; #define PG8_LDB(dst, b, h) do { _Pragma("unroll") for (int n = 0; n < 2; ++n) _Pragma("unroll") for (int k = 0; k < 2; ++k) dst[n][k] = *(const PG8_LAS half8*)(lds + PG8_SB(b, h) + boff + n * 2048 + k * 1024); } while (0)
; #define PG8_MMA(ai, bj, At, Bt) do { __builtin_amdgcn_s_setprio(1); _Pragma("unroll") for (int m = 0; m < 4; ++m) _Pragma("unroll") for (int n = 0; n < 2; ++n) _Pragma("unroll") for (int k = 0; k < 2; ++k) \
;         acc[ai][bj][m][n] = __builtin_amdgcn_mfma_f32_16x16x32_f16(Bt[n][k], At[m][k], acc[ai][bj][m][n], 0, 0, 0); __builtin_amdgcn_s_setprio(0); } while (0)
; #define PG8_WAIT_V(n) asm volatile("s_waitcnt vmcnt(" #n ")" ::: "memory")
; #define PG8_WAIT_L(n) asm volatile("s_waitcnt lgkmcnt(" #n ")" ::: "memory")
; #define PG8_BAR __builtin_amdgcn_s_barrier()
; #define PG8_SCHED __builtin_amdgcn_sched_barrier(0)
; template <class Epi>
; __device__ __forceinline__ void gemm_phase(PG8_LAS unsigned char* lds, const Gemm g, const StaticOrder& S_, const Epi& E) {
;     ...
;             const bool last = (t == nt - 2);
;             const char* a1 = cA + (size_t)(t + 1) * kstep;
;             const char* a2 = last ? nA : cA + (size_t)(t + 2) * kstep; const char* b2 = last ? nB : cB + (size_t)(t + 2) * kstep;
;             const char* a3 = a2 + kstep; const char* b3 = b2 + kstep;
;             PG8_LDB(B0, 0, 0); PG8_LDB(B1, 0, 1); PG8_SCHED; PG8_LDA(At, 0, 0); PG8_STAGE(PG8_SA(1, 1), a1 + hstepA, voffA);
;             PG8_WAIT_V(8); PG8_WAIT_L(0); PG8_BAR; PG8_MMA(0, 0, At, B0); PG8_MMA(0, 1, At, B1); PG8_BAR; PG8_SCHED;
;             PG8_LDA(At, 0, 1); PG8_STAGE(PG8_SB(0, 0), b2, voffB); PG8_STAGE(PG8_SB(0, 1), b2 + hstepB, voffB); PG8_STAGE(PG8_SA(0, 0), a2, voffA);
;             PG8_WAIT_V(8); PG8_WAIT_L(0); PG8_BAR; PG8_MMA(1, 0, At, B0); PG8_MMA(1, 1, At, B1); PG8_BAR; PG8_SCHED;
.LBB0_1307:
	s_add_u32 s2, s56, 0xfffc0080
	s_addc_u32 s3, s57, -1
	s_add_i32 s33, 0, 0x10000
	s_cmp_eq_u32 s88, 12
	s_cselect_b32 s59, s47, s3
	s_cselect_b32 s58, s53, s2
	s_cselect_b32 s3, s45, s84
	s_cselect_b32 s2, s55, s83
	s_add_i32 s94, 0, 0x14000
	v_add_u32_e32 v78, s33, v208
	v_add_u32_e32 v94, s94, v208
	ds_read_b128 v[66:69], v78
	ds_read_b128 v[70:73], v78 offset:1024
	ds_read_b128 v[74:77], v78 offset:2048
	ds_read_b128 v[78:81], v78 offset:3072
	ds_read_b128 v[82:85], v94
	ds_read_b128 v[86:89], v94 offset:1024
	ds_read_b128 v[90:93], v94 offset:2048
	ds_read_b128 v[94:97], v94 offset:3072
	v_lshl_add_u64 v[242:243], s[56:57], 0, v[192:193]
	s_add_i32 m0, s72, 0xc000
	ds_read_b128 v[162:165], v220
	ds_read_b128 v[166:169], v220 offset:1024
	ds_read_b128 v[194:197], v220 offset:2048
	ds_read_b128 v[222:225], v220 offset:3072
	ds_read_b128 v[226:229], v220 offset:4096
	ds_read_b128 v[230:233], v220 offset:5120
	ds_read_b128 v[234:237], v220 offset:6144
	ds_read_b128 v[238:241], v220 offset:7168
	global_load_lds_dwordx4 v[242:243], off
	v_lshl_add_u64 v[242:243], s[56:57], 0, v[190:191]
	s_add_i32 m0, s72, 0xe000
	s_nop 0
	global_load_lds_dwordx4 v[242:243], off
	s_waitcnt vmcnt(8)
	s_waitcnt lgkmcnt(0)
	s_barrier
	s_setprio 1
	s_waitcnt lgkmcnt(0)
	v_mfma_f32_16x16x32_f16 v[158:161], v[66:69], v[162:165], v[158:161]
	v_mfma_f32_16x16x32_f16 v[154:157], v[74:77], v[162:165], v[154:157]
	v_mfma_f32_16x16x32_f16 v[142:145], v[66:69], v[194:197], v[142:145]
	v_mfma_f32_16x16x32_f16 v[134:137], v[74:77], v[194:197], v[134:137]
	v_mfma_f32_16x16x32_f16 v[126:129], v[66:69], v[226:229], v[126:129]
	v_mfma_f32_16x16x32_f16 v[118:121], v[74:77], v[226:229], v[118:121]
	v_mfma_f32_16x16x32_f16 v[106:109], v[66:69], v[234:237], v[106:109]
	v_mfma_f32_16x16x32_f16 v[102:105], v[74:77], v[234:237], v[102:105]
	v_mfma_f32_16x16x32_f16 v[158:161], v[70:73], v[166:169], v[158:161]
	v_mfma_f32_16x16x32_f16 v[154:157], v[78:81], v[166:169], v[154:157]
	v_mfma_f32_16x16x32_f16 v[142:145], v[70:73], v[222:225], v[142:145]
	v_mfma_f32_16x16x32_f16 v[134:137], v[78:81], v[222:225], v[134:137]
	v_mfma_f32_16x16x32_f16 v[126:129], v[70:73], v[230:233], v[126:129]
	v_mfma_f32_16x16x32_f16 v[118:121], v[78:81], v[230:233], v[118:121]
	v_mfma_f32_16x16x32_f16 v[106:109], v[70:73], v[238:241], v[106:109]
	v_mfma_f32_16x16x32_f16 v[102:105], v[78:81], v[238:241], v[102:105]
	s_setprio 0
	s_setprio 1
	v_mfma_f32_16x16x32_f16 v[150:153], v[82:85], v[162:165], v[150:153]
	v_mfma_f32_16x16x32_f16 v[146:149], v[90:93], v[162:165], v[146:149]
	v_mfma_f32_16x16x32_f16 v[138:141], v[82:85], v[194:197], v[138:141]
	v_mfma_f32_16x16x32_f16 v[130:133], v[90:93], v[194:197], v[130:133]
	v_mfma_f32_16x16x32_f16 v[122:125], v[82:85], v[226:229], v[122:125]
	v_mfma_f32_16x16x32_f16 v[114:117], v[90:93], v[226:229], v[114:117]
	v_mfma_f32_16x16x32_f16 v[110:113], v[82:85], v[234:237], v[110:113]
	v_mfma_f32_16x16x32_f16 v[98:101], v[90:93], v[234:237], v[98:101]
	v_mfma_f32_16x16x32_f16 v[150:153], v[86:89], v[166:169], v[150:153]
	v_mfma_f32_16x16x32_f16 v[146:149], v[94:97], v[166:169], v[146:149]
	v_mfma_f32_16x16x32_f16 v[138:141], v[86:89], v[222:225], v[138:141]
	v_mfma_f32_16x16x32_f16 v[130:133], v[94:97], v[222:225], v[130:133]
	v_mfma_f32_16x16x32_f16 v[122:125], v[86:89], v[230:233], v[122:125]
	v_mfma_f32_16x16x32_f16 v[114:117], v[94:97], v[230:233], v[114:117]
	v_mfma_f32_16x16x32_f16 v[110:113], v[86:89], v[238:241], v[110:113]
	v_mfma_f32_16x16x32_f16 v[98:101], v[94:97], v[238:241], v[98:101]
	s_setprio 0
	s_barrier
	s_add_i32 s33, s33, s71
	v_lshl_add_u64 v[242:243], s[2:3], 0, v[0:1]
	s_mov_b32 m0, s33
	ds_read_b128 v[162:165], v220 offset:16384
	ds_read_b128 v[166:169], v220 offset:17408
	ds_read_b128 v[194:197], v220 offset:18432
	ds_read_b128 v[222:225], v220 offset:19456
	ds_read_b128 v[226:229], v220 offset:20480
	ds_read_b128 v[230:233], v220 offset:21504
	ds_read_b128 v[234:237], v220 offset:22528
	ds_read_b128 v[238:241], v220 offset:23552
	global_load_lds_dwordx4 v[242:243], off
	s_add_i32 m0, s33, 0x2000
	s_add_u32 s92, s2, 0x40000
	v_lshl_add_u64 v[244:245], s[2:3], 0, v[184:185]
	s_addc_u32 s93, s3, 0
	s_add_i32 s33, s94, s71
	global_load_lds_dwordx4 v[244:245], off
	v_lshl_add_u64 v[246:247], s[92:93], 0, v[0:1]
	s_mov_b32 m0, s33
	v_lshl_add_u64 v[248:249], s[58:59], 0, v[182:183]
	global_load_lds_dwordx4 v[246:247], off
	v_lshl_add_u64 v[246:247], s[92:93], 0, v[184:185]
	s_add_i32 m0, s33, 0x2000
	s_nop 0
	global_load_lds_dwordx4 v[246:247], off
	v_lshl_add_u64 v[246:247], s[58:59], 0, v[180:181]
	s_mov_b32 m0, s72
	s_nop 0
	global_load_lds_dwordx4 v[246:247], off
	s_mov_b32 m0, s73
	s_nop 0
	global_load_lds_dwordx4 v[248:249], off
	s_waitcnt vmcnt(8)
	s_waitcnt lgkmcnt(0)
	s_barrier
; #define PG8_STAGE(bufoff, gbase, voff) do { _Pragma("unroll") for (int _i = 0; _i < 2; ++_i) \
;         __builtin_amdgcn_global_load_lds((const unsigned*)((const char*)(gbase) + (voff)[_i]), (PG8_LAS unsigned*)(lds + (bufoff) + ldsw + _i * 8192), 16, 0, 0); } while (0)
; #define PG8_LDA(dst, b, h) do { _Pragma("unroll") for (int m = 0; m < 4; ++m) _Pragma("unroll") for (int k = 0; k < 2; ++k) dst[m][k] = *(const PG8_LAS half8*)(lds + PG8_SA(b, h) + aoff + m * 2048 + k * 1024); } while (0)
; #define PG8_LDB(dst, b, h) do { _Pragma("unroll") for (int n = 0; n < 2; ++n) _Pragma("unroll") for (int k = 0; k < 2; ++k) dst[n][k] = *(const PG8_LAS half8*)(lds + PG8_SB(b, h) + boff + n * 2048 + k * 1024); } while (0)
; #define PG8_MMA(ai, bj, At, Bt) do { __builtin_amdgcn_s_setprio(1); _Pragma("unroll") for (int m = 0; m < 4; ++m) _Pragma("unroll") for (int n = 0; n < 2; ++n) _Pragma("unroll") for (int k = 0; k < 2; ++k) \
;         acc[ai][bj][m][n] = __builtin_amdgcn_mfma_f32_16x16x32_f16(Bt[n][k], At[m][k], acc[ai][bj][m][n], 0, 0, 0); __builtin_amdgcn_s_setprio(0); } while (0)
; #define PG8_WAIT_V(n) asm volatile("s_waitcnt vmcnt(" #n ")" ::: "memory")
; #define PG8_WAIT_L(n) asm volatile("s_waitcnt lgkmcnt(" #n ")" ::: "memory")
; #define PG8_BAR __builtin_amdgcn_s_barrier()
; #define PG8_SCHED __builtin_amdgcn_sched_barrier(0)
; template <class Epi>
; __device__ __forceinline__ void gemm_phase(PG8_LAS unsigned char* lds, const Gemm g, const StaticOrder& S_, const Epi& E) {
;     ...
;             PG8_WAIT_V(8); PG8_WAIT_L(0); PG8_BAR; PG8_MMA(1, 0, At, B0); PG8_MMA(1, 1, At, B1); PG8_BAR; PG8_SCHED;
;             PG8_LDB(B0, 1, 0); PG8_LDB(B1, 1, 1); PG8_SCHED; PG8_LDA(At, 1, 0); PG8_STAGE(PG8_SA(0, 1), a2 + hstepA, voffA);
;             PG8_WAIT_V(8); PG8_WAIT_L(0); PG8_BAR; PG8_MMA(0, 0, At, B0); PG8_MMA(0, 1, At, B1); PG8_BAR; PG8_SCHED;
;             PG8_LDA(At, 1, 1); PG8_STAGE(PG8_SB(1, 0), b3, voffB); PG8_STAGE(PG8_SB(1, 1), b3 + hstepB, voffB); PG8_STAGE(PG8_SA(1, 0), a3, voffA);
;             PG8_WAIT_V(8); PG8_WAIT_L(0); PG8_BAR; PG8_MMA(1, 0, At, B0); PG8_MMA(1, 1, At, B1); PG8_BAR; PG8_SCHED;
	s_setprio 1
	s_waitcnt lgkmcnt(0)
	v_mfma_f32_16x16x32_f16 v[62:65], v[66:69], v[162:165], v[62:65]
	v_mfma_f32_16x16x32_f16 v[58:61], v[74:77], v[162:165], v[58:61]
	v_mfma_f32_16x16x32_f16 v[46:49], v[66:69], v[194:197], v[46:49]
	v_mfma_f32_16x16x32_f16 v[38:41], v[74:77], v[194:197], v[38:41]
	v_mfma_f32_16x16x32_f16 v[30:33], v[66:69], v[226:229], v[30:33]
	v_mfma_f32_16x16x32_f16 v[22:25], v[74:77], v[226:229], v[22:25]
	v_mfma_f32_16x16x32_f16 v[10:13], v[66:69], v[234:237], v[10:13]
	v_mfma_f32_16x16x32_f16 v[6:9], v[74:77], v[234:237], v[6:9]
	v_mfma_f32_16x16x32_f16 v[62:65], v[70:73], v[166:169], v[62:65]
	v_mfma_f32_16x16x32_f16 v[58:61], v[78:81], v[166:169], v[58:61]
	v_mfma_f32_16x16x32_f16 v[46:49], v[70:73], v[222:225], v[46:49]
	v_mfma_f32_16x16x32_f16 v[38:41], v[78:81], v[222:225], v[38:41]
	v_mfma_f32_16x16x32_f16 v[30:33], v[70:73], v[230:233], v[30:33]
	v_mfma_f32_16x16x32_f16 v[22:25], v[78:81], v[230:233], v[22:25]
	v_mfma_f32_16x16x32_f16 v[10:13], v[70:73], v[238:241], v[10:13]
	v_mfma_f32_16x16x32_f16 v[6:9], v[78:81], v[238:241], v[6:9]
	s_setprio 0
	s_setprio 1
	v_mfma_f32_16x16x32_f16 v[54:57], v[82:85], v[162:165], v[54:57]
	v_mfma_f32_16x16x32_f16 v[50:53], v[90:93], v[162:165], v[50:53]
	v_mfma_f32_16x16x32_f16 v[42:45], v[82:85], v[194:197], v[42:45]
	v_mfma_f32_16x16x32_f16 v[34:37], v[90:93], v[194:197], v[34:37]
	v_mfma_f32_16x16x32_f16 v[26:29], v[82:85], v[226:229], v[26:29]
	v_mfma_f32_16x16x32_f16 v[18:21], v[90:93], v[226:229], v[18:21]
	v_mfma_f32_16x16x32_f16 v[14:17], v[82:85], v[234:237], v[14:17]
	v_mfma_f32_16x16x32_f16 v[2:5], v[90:93], v[234:237], v[2:5]
	v_mfma_f32_16x16x32_f16 v[54:57], v[86:89], v[166:169], v[54:57]
	v_mfma_f32_16x16x32_f16 v[50:53], v[94:97], v[166:169], v[50:53]
	v_mfma_f32_16x16x32_f16 v[42:45], v[86:89], v[222:225], v[42:45]
	v_mfma_f32_16x16x32_f16 v[34:37], v[94:97], v[222:225], v[34:37]
	v_mfma_f32_16x16x32_f16 v[26:29], v[86:89], v[230:233], v[26:29]
	v_mfma_f32_16x16x32_f16 v[18:21], v[94:97], v[230:233], v[18:21]
	v_mfma_f32_16x16x32_f16 v[14:17], v[86:89], v[238:241], v[14:17]
	v_mfma_f32_16x16x32_f16 v[2:5], v[94:97], v[238:241], v[2:5]
	s_setprio 0
	s_barrier
	s_add_i32 s33, 0, 0x18000
	s_add_i32 s92, 0, 0x1c000
	v_add_u32_e32 v78, s33, v208
	v_add_u32_e32 v94, s92, v208
	ds_read_b128 v[66:69], v78
	ds_read_b128 v[70:73], v78 offset:1024
	ds_read_b128 v[74:77], v78 offset:2048
	ds_read_b128 v[78:81], v78 offset:3072
	ds_read_b128 v[82:85], v94
	ds_read_b128 v[86:89], v94 offset:1024
	ds_read_b128 v[90:93], v94 offset:2048
	ds_read_b128 v[94:97], v94 offset:3072
	s_add_u32 s58, s58, 0x40000
	s_addc_u32 s59, s59, 0
	s_mov_b32 m0, s74
	v_lshl_add_u64 v[250:251], s[58:59], 0, v[180:181]
	ds_read_b128 v[162:165], v220 offset:32768
	ds_read_b128 v[166:169], v220 offset:33792
	ds_read_b128 v[194:197], v220 offset:34816
	ds_read_b128 v[222:225], v220 offset:35840
	ds_read_b128 v[226:229], v220 offset:36864
	ds_read_b128 v[230:233], v220 offset:37888
	ds_read_b128 v[234:237], v220 offset:38912
	ds_read_b128 v[238:241], v220 offset:39936
	global_load_lds_dwordx4 v[250:251], off
	v_lshl_add_u64 v[250:251], s[58:59], 0, v[182:183]
	s_mov_b32 m0, s75
	s_nop 0
	global_load_lds_dwordx4 v[250:251], off
	s_waitcnt vmcnt(8)
	s_waitcnt lgkmcnt(0)
	s_barrier
	s_setprio 1
	s_waitcnt lgkmcnt(0)
	v_mfma_f32_16x16x32_f16 v[158:161], v[66:69], v[162:165], v[158:161]
	v_mfma_f32_16x16x32_f16 v[154:157], v[74:77], v[162:165], v[154:157]
	v_mfma_f32_16x16x32_f16 v[142:145], v[66:69], v[194:197], v[142:145]
	v_mfma_f32_16x16x32_f16 v[134:137], v[74:77], v[194:197], v[134:137]
	v_mfma_f32_16x16x32_f16 v[126:129], v[66:69], v[226:229], v[126:129]
	v_mfma_f32_16x16x32_f16 v[118:121], v[74:77], v[226:229], v[118:121]
	v_mfma_f32_16x16x32_f16 v[106:109], v[66:69], v[234:237], v[106:109]
	v_mfma_f32_16x16x32_f16 v[102:105], v[74:77], v[234:237], v[102:105]
	v_mfma_f32_16x16x32_f16 v[158:161], v[70:73], v[166:169], v[158:161]
	v_mfma_f32_16x16x32_f16 v[154:157], v[78:81], v[166:169], v[154:157]
	v_mfma_f32_16x16x32_f16 v[142:145], v[70:73], v[222:225], v[142:145]
	v_mfma_f32_16x16x32_f16 v[134:137], v[78:81], v[222:225], v[134:137]
	v_mfma_f32_16x16x32_f16 v[126:129], v[70:73], v[230:233], v[126:129]
	v_mfma_f32_16x16x32_f16 v[118:121], v[78:81], v[230:233], v[118:121]
	v_mfma_f32_16x16x32_f16 v[106:109], v[70:73], v[238:241], v[106:109]
	v_mfma_f32_16x16x32_f16 v[102:105], v[78:81], v[238:241], v[102:105]
	s_setprio 0
	s_setprio 1
	v_mfma_f32_16x16x32_f16 v[150:153], v[82:85], v[162:165], v[150:153]
	v_mfma_f32_16x16x32_f16 v[146:149], v[90:93], v[162:165], v[146:149]
	v_mfma_f32_16x16x32_f16 v[138:141], v[82:85], v[194:197], v[138:141]
	v_mfma_f32_16x16x32_f16 v[130:133], v[90:93], v[194:197], v[130:133]
	v_mfma_f32_16x16x32_f16 v[122:125], v[82:85], v[226:229], v[122:125]
	v_mfma_f32_16x16x32_f16 v[114:117], v[90:93], v[226:229], v[114:117]
	v_mfma_f32_16x16x32_f16 v[110:113], v[82:85], v[234:237], v[110:113]
	v_mfma_f32_16x16x32_f16 v[98:101], v[90:93], v[234:237], v[98:101]
	v_mfma_f32_16x16x32_f16 v[150:153], v[86:89], v[166:169], v[150:153]
	v_mfma_f32_16x16x32_f16 v[146:149], v[94:97], v[166:169], v[146:149]
	v_mfma_f32_16x16x32_f16 v[138:141], v[86:89], v[222:225], v[138:141]
	v_mfma_f32_16x16x32_f16 v[130:133], v[94:97], v[222:225], v[130:133]
	v_mfma_f32_16x16x32_f16 v[122:125], v[86:89], v[230:233], v[122:125]
	v_mfma_f32_16x16x32_f16 v[114:117], v[94:97], v[230:233], v[114:117]
	v_mfma_f32_16x16x32_f16 v[110:113], v[86:89], v[238:241], v[110:113]
	v_mfma_f32_16x16x32_f16 v[98:101], v[94:97], v[238:241], v[98:101]
	s_setprio 0
	s_barrier
; #define PG8_LAS __attribute__((address_space(3)))
; #define PG8_STAGE(bufoff, gbase, voff) do { _Pragma("unroll") for (int _i = 0; _i < 2; ++_i) \
;         __builtin_amdgcn_global_load_lds((const unsigned*)((const char*)(gbase) + (voff)[_i]), (PG8_LAS unsigned*)(lds + (bufoff) + ldsw + _i * 8192), 16, 0, 0); } while (0)
; #define PG8_LDA(dst, b, h) do { _Pragma("unroll") for (int m = 0; m < 4; ++m) _Pragma("unroll") for (int k = 0; k < 2; ++k) dst[m][k] = *(const PG8_LAS half8*)(lds + PG8_SA(b, h) + aoff + m * 2048 + k * 1024); } while (0)
; #define PG8_MMA(ai, bj, At, Bt) do { __builtin_amdgcn_s_setprio(1); _Pragma("unroll") for (int m = 0; m < 4; ++m) _Pragma("unroll") for (int n = 0; n < 2; ++n) _Pragma("unroll") for (int k = 0; k < 2; ++k) \
;         acc[ai][bj][m][n] = __builtin_amdgcn_mfma_f32_16x16x32_f16(Bt[n][k], At[m][k], acc[ai][bj][m][n], 0, 0, 0); __builtin_amdgcn_s_setprio(0); } while (0)
;     __device__ __forceinline__ void operator()(const f32x4 (&acc)[2][2][4][2], const Unit& u, int wr, int wc, int fr, int fq, PG8_LAS unsigned char* lds) const {
;     ...
;         const int j0 = u.pn * 128 + wc * 32 + 8 * fq;
; #pragma unroll
;         for (int ai = 0; ai < 2; ++ai)
;             if (fr >= 14) { PG8_LAS float* h = halo + ((((ai * 2 + wr) * 4 + wc) * 2 + (fr - 14)) * 32 + fq * 8);
;                 *(PG8_LAS f32x4*)h = acc[ai][0][3][0]; *(PG8_LAS f32x4*)(h + 4) = acc[ai][0][3][1]; }
;         asm volatile("s_waitcnt lgkmcnt(0)" ::: "memory"); __builtin_amdgcn_s_barrier(); asm volatile("" ::: "memory");
;         float w0[8], w1[8], w2[8], bb[8];
;         { const f32x4 a0 = *(const f32x4*)(cw + j0), a1 = *(const f32x4*)(cw + j0 + 4), b0 = *(const f32x4*)(cw + DFF + j0), b1 = *(const f32x4*)(cw + DFF + j0 + 4);
;           const f32x4 c0 = *(const f32x4*)(cw + 2 * DFF + j0), c1 = *(const f32x4*)(cw + 2 * DFF + j0 + 4), d0 = *(const f32x4*)(cb + j0), d1 = *(const f32x4*)(cb + j0 + 4);
; template <class Epi>
; __device__ __forceinline__ void gemm_phase(PG8_LAS unsigned char* lds, const Gemm g, const StaticOrder& S_, const Epi& E) {
;     ...
;             PG8_LDA(At, 1, 1); PG8_STAGE(PG8_SB(1, 0), b3, voffB); PG8_STAGE(PG8_SB(1, 1), b3 + hstepB, voffB); PG8_STAGE(PG8_SA(1, 0), a3, voffA);
;             PG8_WAIT_V(8); PG8_WAIT_L(0); PG8_BAR; PG8_MMA(1, 0, At, B0); PG8_MMA(1, 1, At, B1); PG8_BAR; PG8_SCHED;
;         }
;         if (wr == 0) PG8_BAR;
	s_add_i32 s33, s33, s71
	v_lshl_add_u64 v[242:243], v[242:243], 0, s[86:87]
	s_mov_b32 m0, s33
	ds_read_b128 v[162:165], v220 offset:49152
	ds_read_b128 v[166:169], v220 offset:50176
	ds_read_b128 v[194:197], v220 offset:51200
	ds_read_b128 v[222:225], v220 offset:52224
	ds_read_b128 v[226:229], v220 offset:53248
	ds_read_b128 v[230:233], v220 offset:54272
	ds_read_b128 v[234:237], v220 offset:55296
	ds_read_b128 v[238:241], v220 offset:56320
	global_load_lds_dwordx4 v[242:243], off
	s_add_i32 m0, s33, 0x2000
	s_add_u32 s2, s2, 0x40080
	v_lshl_add_u64 v[242:243], v[244:245], 0, s[86:87]
	s_addc_u32 s3, s3, 0
	s_add_i32 s33, s92, s71
	global_load_lds_dwordx4 v[242:243], off
	v_lshl_add_u64 v[242:243], s[2:3], 0, v[0:1]
	s_mov_b32 m0, s33
	s_nop 0
	global_load_lds_dwordx4 v[242:243], off
	v_lshl_add_u64 v[242:243], s[2:3], 0, v[184:185]
	s_add_i32 m0, s33, 0x2000
	s_nop 0
	global_load_lds_dwordx4 v[242:243], off
	v_lshl_add_u64 v[242:243], v[246:247], 0, s[86:87]
	s_mov_b32 m0, s77
	s_nop 0
	global_load_lds_dwordx4 v[242:243], off
	v_lshl_add_u64 v[242:243], v[248:249], 0, s[86:87]
	s_mov_b32 m0, s78
	s_nop 0
	global_load_lds_dwordx4 v[242:243], off
	s_waitcnt vmcnt(8)
	s_waitcnt lgkmcnt(0)
	s_barrier
	s_setprio 1
	s_waitcnt lgkmcnt(0)
	v_mfma_f32_16x16x32_f16 v[62:65], v[66:69], v[162:165], v[62:65]
	v_mfma_f32_16x16x32_f16 v[58:61], v[74:77], v[162:165], v[58:61]
	v_mfma_f32_16x16x32_f16 v[46:49], v[66:69], v[194:197], v[46:49]
	v_mfma_f32_16x16x32_f16 v[38:41], v[74:77], v[194:197], v[38:41]
	v_mfma_f32_16x16x32_f16 v[30:33], v[66:69], v[226:229], v[30:33]
	v_mfma_f32_16x16x32_f16 v[22:25], v[74:77], v[226:229], v[22:25]
	v_mfma_f32_16x16x32_f16 v[10:13], v[66:69], v[234:237], v[10:13]
	v_mfma_f32_16x16x32_f16 v[6:9], v[74:77], v[234:237], v[6:9]
	v_mfma_f32_16x16x32_f16 v[62:65], v[70:73], v[166:169], v[62:65]
	v_mfma_f32_16x16x32_f16 v[58:61], v[78:81], v[166:169], v[58:61]
	v_mfma_f32_16x16x32_f16 v[46:49], v[70:73], v[222:225], v[46:49]
	v_mfma_f32_16x16x32_f16 v[38:41], v[78:81], v[222:225], v[38:41]
	v_mfma_f32_16x16x32_f16 v[30:33], v[70:73], v[230:233], v[30:33]
	v_mfma_f32_16x16x32_f16 v[22:25], v[78:81], v[230:233], v[22:25]
	v_mfma_f32_16x16x32_f16 v[10:13], v[70:73], v[238:241], v[10:13]
	v_mfma_f32_16x16x32_f16 v[6:9], v[78:81], v[238:241], v[6:9]
	s_setprio 0
	s_setprio 1
	v_mfma_f32_16x16x32_f16 v[54:57], v[82:85], v[162:165], v[54:57]
	v_mfma_f32_16x16x32_f16 v[50:53], v[90:93], v[162:165], v[50:53]
	v_mfma_f32_16x16x32_f16 v[42:45], v[82:85], v[194:197], v[42:45]
	v_mfma_f32_16x16x32_f16 v[34:37], v[90:93], v[194:197], v[34:37]
	v_mfma_f32_16x16x32_f16 v[26:29], v[82:85], v[226:229], v[26:29]
	v_mfma_f32_16x16x32_f16 v[18:21], v[90:93], v[226:229], v[18:21]
	v_mfma_f32_16x16x32_f16 v[14:17], v[82:85], v[234:237], v[14:17]
	v_mfma_f32_16x16x32_f16 v[2:5], v[90:93], v[234:237], v[2:5]
	v_mfma_f32_16x16x32_f16 v[54:57], v[86:89], v[166:169], v[54:57]
	v_mfma_f32_16x16x32_f16 v[50:53], v[94:97], v[166:169], v[50:53]
	v_mfma_f32_16x16x32_f16 v[42:45], v[86:89], v[222:225], v[42:45]
	v_mfma_f32_16x16x32_f16 v[34:37], v[94:97], v[222:225], v[34:37]
	v_mfma_f32_16x16x32_f16 v[26:29], v[86:89], v[230:233], v[26:29]
	v_mfma_f32_16x16x32_f16 v[18:21], v[94:97], v[230:233], v[18:21]
	v_mfma_f32_16x16x32_f16 v[14:17], v[86:89], v[238:241], v[14:17]
	v_mfma_f32_16x16x32_f16 v[2:5], v[94:97], v[238:241], v[2:5]
	s_setprio 0
	s_add_i32 s88, s88, 2
	s_add_u32 s83, s83, 0x100
	s_addc_u32 s84, s84, 0
	s_add_u32 s56, s56, 0x100
	s_addc_u32 s57, s57, 0
	s_cmp_gt_u32 s88, 13
	s_barrier
	s_cbranch_scc0 .LBB0_1307
	v_lshl_or_b32 v194, s54, 7, v219
	v_ashrrev_i32_e32 v195, 31, v194
	v_lshlrev_b64 v[196:197], 2, v[194:195]
	v_lshl_add_u64 v[70:71], s[16:17], 0, v[196:197]
	v_lshl_add_u64 v[74:75], s[40:41], 0, v[196:197]
	v_lshl_add_u64 v[78:79], s[42:43], 0, v[196:197]
	v_lshl_add_u64 v[94:95], s[18:19], 0, v[196:197]
	global_load_dwordx4 v[66:69], v[70:71], off offset:16
	global_load_dwordx4 v[82:85], v[70:71], off
	s_nop 0
	global_load_dwordx4 v[70:73], v[74:75], off offset:16
	global_load_dwordx4 v[86:89], v[74:75], off
	s_nop 0
	global_load_dwordx4 v[74:77], v[78:79], off offset:16
	global_load_dwordx4 v[90:93], v[78:79], off
	s_nop 0
	global_load_dwordx4 v[78:81], v[94:95], off offset:16
	s_nop 0
	global_load_dwordx4 v[94:97], v[94:95], off
	s_and_b64 vcc, exec, s[24:25]
	s_cbranch_vccz .LBB0_1310
	s_barrier

; #define PG8_STAGE(bufoff, gbase, voff) do { _Pragma("unroll") for (int _i = 0; _i < 2; ++_i) \
;         __builtin_amdgcn_global_load_lds((const unsigned*)((const char*)(gbase) + (voff)[_i]), (PG8_LAS unsigned*)(lds + (bufoff) + ldsw + _i * 8192), 16, 0, 0); } while (0)
; #define PG8_LDA(dst, b, h) do { _Pragma("unroll") for (int m = 0; m < 4; ++m) _Pragma("unroll") for (int k = 0; k < 2; ++k) dst[m][k] = *(const PG8_LAS half8*)(lds + PG8_SA(b, h) + aoff + m * 2048 + k * 1024); } while (0)
; #define PG8_LDB(dst, b, h) do { _Pragma("unroll") for (int n = 0; n < 2; ++n) _Pragma("unroll") for (int k = 0; k < 2; ++k) dst[n][k] = *(const PG8_LAS half8*)(lds + PG8_SB(b, h) + boff + n * 2048 + k * 1024); } while (0)
; #define PG8_MMA(ai, bj, At, Bt) do { __builtin_amdgcn_s_setprio(1); _Pragma("unroll") for (int m = 0; m < 4; ++m) _Pragma("unroll") for (int n = 0; n < 2; ++n) _Pragma("unroll") for (int k = 0; k < 2; ++k) \
;         acc[ai][bj][m][n] = __builtin_amdgcn_mfma_f32_16x16x32_f16(Bt[n][k], At[m][k], acc[ai][bj][m][n], 0, 0, 0); __builtin_amdgcn_s_setprio(0); } while (0)
; #define PG8_WAIT_V(n) asm volatile("s_waitcnt vmcnt(" #n ")" ::: "memory")
; #define PG8_WAIT_L(n) asm volatile("s_waitcnt lgkmcnt(" #n ")" ::: "memory")
; #define PG8_BAR __builtin_amdgcn_s_barrier()
; #define PG8_SCHED __builtin_amdgcn_sched_barrier(0)
; template <class Epi>
; __device__ __forceinline__ void gemm_phase(PG8_LAS unsigned char* lds, const Gemm g, const StaticOrder& S_, const Epi& E) {
;     ...
;             const bool last = (t == nt - 2);
;             const char* a1 = cA + (size_t)(t + 1) * kstep;
;             const char* a2 = last ? nA : cA + (size_t)(t + 2) * kstep; const char* b2 = last ? nB : cB + (size_t)(t + 2) * kstep;
;             const char* a3 = a2 + kstep; const char* b3 = b2 + kstep;
;             PG8_LDB(B0, 0, 0); PG8_LDB(B1, 0, 1); PG8_SCHED; PG8_LDA(At, 0, 0); PG8_STAGE(PG8_SA(1, 1), a1 + hstepA, voffA);
;             PG8_WAIT_V(8); PG8_WAIT_L(0); PG8_BAR; PG8_MMA(0, 0, At, B0); PG8_MMA(0, 1, At, B1); PG8_BAR; PG8_SCHED;
;             PG8_LDA(At, 0, 1); PG8_STAGE(PG8_SB(0, 0), b2, voffB); PG8_STAGE(PG8_SB(0, 1), b2 + hstepB, voffB); PG8_STAGE(PG8_SA(0, 0), a2, voffA);
;             PG8_WAIT_V(8); PG8_WAIT_L(0); PG8_BAR; PG8_MMA(1, 0, At, B0); PG8_MMA(1, 1, At, B1); PG8_BAR; PG8_SCHED;
.LBB0_1475:
	s_add_u32 s2, s16, 0x100
	s_addc_u32 s3, s17, 0
	s_add_i32 s33, 0, 0x10000
	s_cmp_eq_u32 s44, 40
	s_cselect_b32 s21, s7, s3
	s_cselect_b32 s20, s6, s2
	s_cselect_b32 s19, s15, s43
	s_cselect_b32 s18, s14, s42
	s_add_i32 s45, 0, 0x14000
	v_add_u32_e32 v156, s33, v141
	v_add_u32_e32 v168, s45, v141
	ds_read_b128 v[144:147], v156
	ds_read_b128 v[148:151], v156 offset:1024
	ds_read_b128 v[152:155], v156 offset:2048
	ds_read_b128 v[156:159], v156 offset:3072
	ds_read_b128 v[160:163], v168
	ds_read_b128 v[164:167], v168 offset:1024
	ds_read_b128 v[180:183], v168 offset:2048
	ds_read_b128 v[184:187], v168 offset:3072
	v_lshl_add_u64 v[168:169], s[16:17], 0, v[138:139]
	s_add_i32 m0, s29, 0xc000
	ds_read_b128 v[188:191], v143
	ds_read_b128 v[192:195], v143 offset:1024
	ds_read_b128 v[208:211], v143 offset:2048
	ds_read_b128 v[212:215], v143 offset:3072
	ds_read_b128 v[216:219], v143 offset:4096
	ds_read_b128 v[220:223], v143 offset:5120
	ds_read_b128 v[224:227], v143 offset:6144
	ds_read_b128 v[228:231], v143 offset:7168
	global_load_lds_dwordx4 v[168:169], off
	v_lshl_add_u64 v[168:169], s[16:17], 0, v[136:137]
	s_add_i32 m0, s29, 0xe000
	s_nop 0
	global_load_lds_dwordx4 v[168:169], off
	s_waitcnt vmcnt(8)
	s_waitcnt lgkmcnt(0)
	s_barrier
	s_setprio 1
	s_waitcnt lgkmcnt(0)
	v_mfma_f32_16x16x32_f16 v[126:129], v[144:147], v[188:191], v[126:129]
	v_mfma_f32_16x16x32_f16 v[122:125], v[152:155], v[188:191], v[122:125]
	v_mfma_f32_16x16x32_f16 v[118:121], v[144:147], v[208:211], v[118:121]
	v_mfma_f32_16x16x32_f16 v[114:117], v[152:155], v[208:211], v[114:117]
	v_mfma_f32_16x16x32_f16 v[102:105], v[144:147], v[216:219], v[102:105]
	v_mfma_f32_16x16x32_f16 v[98:101], v[152:155], v[216:219], v[98:101]
	v_mfma_f32_16x16x32_f16 v[86:89], v[144:147], v[224:227], v[86:89]
	v_mfma_f32_16x16x32_f16 v[82:85], v[152:155], v[224:227], v[82:85]
	v_mfma_f32_16x16x32_f16 v[126:129], v[148:151], v[192:195], v[126:129]
	v_mfma_f32_16x16x32_f16 v[122:125], v[156:159], v[192:195], v[122:125]
	v_mfma_f32_16x16x32_f16 v[118:121], v[148:151], v[212:215], v[118:121]
	v_mfma_f32_16x16x32_f16 v[114:117], v[156:159], v[212:215], v[114:117]
	v_mfma_f32_16x16x32_f16 v[102:105], v[148:151], v[220:223], v[102:105]
	v_mfma_f32_16x16x32_f16 v[98:101], v[156:159], v[220:223], v[98:101]
	v_mfma_f32_16x16x32_f16 v[86:89], v[148:151], v[228:231], v[86:89]
	v_mfma_f32_16x16x32_f16 v[82:85], v[156:159], v[228:231], v[82:85]
	s_setprio 0
	s_setprio 1
	v_mfma_f32_16x16x32_f16 v[110:113], v[160:163], v[188:191], v[110:113]
	v_mfma_f32_16x16x32_f16 v[106:109], v[180:183], v[188:191], v[106:109]
	v_mfma_f32_16x16x32_f16 v[94:97], v[160:163], v[208:211], v[94:97]
	v_mfma_f32_16x16x32_f16 v[90:93], v[180:183], v[208:211], v[90:93]
	v_mfma_f32_16x16x32_f16 v[78:81], v[160:163], v[216:219], v[78:81]
	v_mfma_f32_16x16x32_f16 v[74:77], v[180:183], v[216:219], v[74:77]
	v_mfma_f32_16x16x32_f16 v[70:73], v[160:163], v[224:227], v[70:73]
	v_mfma_f32_16x16x32_f16 v[66:69], v[180:183], v[224:227], v[66:69]
	v_mfma_f32_16x16x32_f16 v[110:113], v[164:167], v[192:195], v[110:113]
	v_mfma_f32_16x16x32_f16 v[106:109], v[184:187], v[192:195], v[106:109]
	v_mfma_f32_16x16x32_f16 v[94:97], v[164:167], v[212:215], v[94:97]
	v_mfma_f32_16x16x32_f16 v[90:93], v[184:187], v[212:215], v[90:93]
	v_mfma_f32_16x16x32_f16 v[78:81], v[164:167], v[220:223], v[78:81]
	v_mfma_f32_16x16x32_f16 v[74:77], v[184:187], v[220:223], v[74:77]
	v_mfma_f32_16x16x32_f16 v[70:73], v[164:167], v[228:231], v[70:73]
	v_mfma_f32_16x16x32_f16 v[66:69], v[184:187], v[228:231], v[66:69]
	s_setprio 0
	s_barrier
	s_add_i32 s16, s33, s28
	v_lshl_add_u64 v[168:169], s[18:19], 0, v[0:1]
	s_mov_b32 m0, s16
	ds_read_b128 v[188:191], v143 offset:16384
	ds_read_b128 v[192:195], v143 offset:17408
	ds_read_b128 v[208:211], v143 offset:18432
	ds_read_b128 v[212:215], v143 offset:19456
	ds_read_b128 v[216:219], v143 offset:20480
	ds_read_b128 v[220:223], v143 offset:21504
	ds_read_b128 v[224:227], v143 offset:22528
	ds_read_b128 v[228:231], v143 offset:23552
	global_load_lds_dwordx4 v[168:169], off
	s_add_i32 m0, s16, 0x2000
	s_add_u32 s16, s18, 0xb0000
	v_lshl_add_u64 v[196:197], s[18:19], 0, v[134:135]
	s_addc_u32 s17, s19, 0
	s_add_i32 s33, s45, s28
	global_load_lds_dwordx4 v[196:197], off
	v_lshl_add_u64 v[232:233], s[16:17], 0, v[0:1]
	s_mov_b32 m0, s33
	v_lshl_add_u64 v[234:235], s[20:21], 0, v[132:133]
	global_load_lds_dwordx4 v[232:233], off
	v_lshl_add_u64 v[232:233], s[16:17], 0, v[134:135]
	s_add_i32 m0, s33, 0x2000
	s_nop 0
	global_load_lds_dwordx4 v[232:233], off
	v_lshl_add_u64 v[232:233], s[20:21], 0, v[130:131]
	s_mov_b32 m0, s29
	s_nop 0
	global_load_lds_dwordx4 v[232:233], off
	s_mov_b32 m0, s30
	s_nop 0
	global_load_lds_dwordx4 v[234:235], off
	s_waitcnt vmcnt(8)
	s_waitcnt lgkmcnt(0)
	s_barrier
; #define PG8_STAGE(bufoff, gbase, voff) do { _Pragma("unroll") for (int _i = 0; _i < 2; ++_i) \
;         __builtin_amdgcn_global_load_lds((const unsigned*)((const char*)(gbase) + (voff)[_i]), (PG8_LAS unsigned*)(lds + (bufoff) + ldsw + _i * 8192), 16, 0, 0); } while (0)
; #define PG8_LDA(dst, b, h) do { _Pragma("unroll") for (int m = 0; m < 4; ++m) _Pragma("unroll") for (int k = 0; k < 2; ++k) dst[m][k] = *(const PG8_LAS half8*)(lds + PG8_SA(b, h) + aoff + m * 2048 + k * 1024); } while (0)
; #define PG8_LDB(dst, b, h) do { _Pragma("unroll") for (int n = 0; n < 2; ++n) _Pragma("unroll") for (int k = 0; k < 2; ++k) dst[n][k] = *(const PG8_LAS half8*)(lds + PG8_SB(b, h) + boff + n * 2048 + k * 1024); } while (0)
; #define PG8_MMA(ai, bj, At, Bt) do { __builtin_amdgcn_s_setprio(1); _Pragma("unroll") for (int m = 0; m < 4; ++m) _Pragma("unroll") for (int n = 0; n < 2; ++n) _Pragma("unroll") for (int k = 0; k < 2; ++k) \
;         acc[ai][bj][m][n] = __builtin_amdgcn_mfma_f32_16x16x32_f16(Bt[n][k], At[m][k], acc[ai][bj][m][n], 0, 0, 0); __builtin_amdgcn_s_setprio(0); } while (0)
; #define PG8_WAIT_V(n) asm volatile("s_waitcnt vmcnt(" #n ")" ::: "memory")
; #define PG8_WAIT_L(n) asm volatile("s_waitcnt lgkmcnt(" #n ")" ::: "memory")
; #define PG8_BAR __builtin_amdgcn_s_barrier()
; #define PG8_SCHED __builtin_amdgcn_sched_barrier(0)
; template <class Epi>
; __device__ __forceinline__ void gemm_phase(PG8_LAS unsigned char* lds, const Gemm g, const StaticOrder& S_, const Epi& E) {
;     ...
;             PG8_WAIT_V(8); PG8_WAIT_L(0); PG8_BAR; PG8_MMA(1, 0, At, B0); PG8_MMA(1, 1, At, B1); PG8_BAR; PG8_SCHED;
;             PG8_LDB(B0, 1, 0); PG8_LDB(B1, 1, 1); PG8_SCHED; PG8_LDA(At, 1, 0); PG8_STAGE(PG8_SA(0, 1), a2 + hstepA, voffA);
;             PG8_WAIT_V(8); PG8_WAIT_L(0); PG8_BAR; PG8_MMA(0, 0, At, B0); PG8_MMA(0, 1, At, B1); PG8_BAR; PG8_SCHED;
;             PG8_LDA(At, 1, 1); PG8_STAGE(PG8_SB(1, 0), b3, voffB); PG8_STAGE(PG8_SB(1, 1), b3 + hstepB, voffB); PG8_STAGE(PG8_SA(1, 0), a3, voffA);
;             PG8_WAIT_V(8); PG8_WAIT_L(0); PG8_BAR; PG8_MMA(1, 0, At, B0); PG8_MMA(1, 1, At, B1); PG8_BAR; PG8_SCHED;
	s_setprio 1
	s_waitcnt lgkmcnt(0)
	v_mfma_f32_16x16x32_f16 v[62:65], v[144:147], v[188:191], v[62:65]
	v_mfma_f32_16x16x32_f16 v[58:61], v[152:155], v[188:191], v[58:61]
	v_mfma_f32_16x16x32_f16 v[54:57], v[144:147], v[208:211], v[54:57]
	v_mfma_f32_16x16x32_f16 v[50:53], v[152:155], v[208:211], v[50:53]
	v_mfma_f32_16x16x32_f16 v[38:41], v[144:147], v[216:219], v[38:41]
	v_mfma_f32_16x16x32_f16 v[34:37], v[152:155], v[216:219], v[34:37]
	v_mfma_f32_16x16x32_f16 v[22:25], v[144:147], v[224:227], v[22:25]
	v_mfma_f32_16x16x32_f16 v[18:21], v[152:155], v[224:227], v[18:21]
	v_mfma_f32_16x16x32_f16 v[62:65], v[148:151], v[192:195], v[62:65]
	v_mfma_f32_16x16x32_f16 v[58:61], v[156:159], v[192:195], v[58:61]
	v_mfma_f32_16x16x32_f16 v[54:57], v[148:151], v[212:215], v[54:57]
	v_mfma_f32_16x16x32_f16 v[50:53], v[156:159], v[212:215], v[50:53]
	v_mfma_f32_16x16x32_f16 v[38:41], v[148:151], v[220:223], v[38:41]
	v_mfma_f32_16x16x32_f16 v[34:37], v[156:159], v[220:223], v[34:37]
	v_mfma_f32_16x16x32_f16 v[22:25], v[148:151], v[228:231], v[22:25]
	v_mfma_f32_16x16x32_f16 v[18:21], v[156:159], v[228:231], v[18:21]
	s_setprio 0
	s_setprio 1
	v_mfma_f32_16x16x32_f16 v[46:49], v[160:163], v[188:191], v[46:49]
	v_mfma_f32_16x16x32_f16 v[42:45], v[180:183], v[188:191], v[42:45]
	v_mfma_f32_16x16x32_f16 v[30:33], v[160:163], v[208:211], v[30:33]
	v_mfma_f32_16x16x32_f16 v[26:29], v[180:183], v[208:211], v[26:29]
	v_mfma_f32_16x16x32_f16 v[14:17], v[160:163], v[216:219], v[14:17]
	v_mfma_f32_16x16x32_f16 v[10:13], v[180:183], v[216:219], v[10:13]
	v_mfma_f32_16x16x32_f16 v[6:9], v[160:163], v[224:227], v[6:9]
	v_mfma_f32_16x16x32_f16 v[2:5], v[180:183], v[224:227], v[2:5]
	v_mfma_f32_16x16x32_f16 v[46:49], v[164:167], v[192:195], v[46:49]
	v_mfma_f32_16x16x32_f16 v[42:45], v[184:187], v[192:195], v[42:45]
	v_mfma_f32_16x16x32_f16 v[30:33], v[164:167], v[212:215], v[30:33]
	v_mfma_f32_16x16x32_f16 v[26:29], v[184:187], v[212:215], v[26:29]
	v_mfma_f32_16x16x32_f16 v[14:17], v[164:167], v[220:223], v[14:17]
	v_mfma_f32_16x16x32_f16 v[10:13], v[184:187], v[220:223], v[10:13]
	v_mfma_f32_16x16x32_f16 v[6:9], v[164:167], v[228:231], v[6:9]
	v_mfma_f32_16x16x32_f16 v[2:5], v[184:187], v[228:231], v[2:5]
	s_setprio 0
	s_barrier
	s_add_i32 s33, 0, 0x18000
	s_add_i32 s45, 0, 0x1c000
	v_add_u32_e32 v156, s33, v141
	v_add_u32_e32 v173, s45, v141
	ds_read_b128 v[144:147], v156
	ds_read_b128 v[148:151], v156 offset:1024
	ds_read_b128 v[152:155], v156 offset:2048
	ds_read_b128 v[156:159], v156 offset:3072
	ds_read_b128 v[160:163], v173
	ds_read_b128 v[164:167], v173 offset:1024
	ds_read_b128 v[180:183], v173 offset:2048
	ds_read_b128 v[184:187], v173 offset:3072
	s_add_u32 s16, s20, 0xb0000
	s_addc_u32 s17, s21, 0
	s_mov_b32 m0, s31
	v_lshl_add_u64 v[236:237], s[16:17], 0, v[130:131]
	ds_read_b128 v[188:191], v143 offset:32768
	ds_read_b128 v[192:195], v143 offset:33792
	ds_read_b128 v[208:211], v143 offset:34816
	ds_read_b128 v[212:215], v143 offset:35840
	ds_read_b128 v[216:219], v143 offset:36864
	ds_read_b128 v[220:223], v143 offset:37888
	ds_read_b128 v[224:227], v143 offset:38912
	ds_read_b128 v[228:231], v143 offset:39936
	global_load_lds_dwordx4 v[236:237], off
	v_lshl_add_u64 v[236:237], s[16:17], 0, v[132:133]
	s_mov_b32 m0, s34
	s_nop 0
	global_load_lds_dwordx4 v[236:237], off
	s_waitcnt vmcnt(8)
	s_waitcnt lgkmcnt(0)
	s_barrier
	s_setprio 1
	s_waitcnt lgkmcnt(0)
	v_mfma_f32_16x16x32_f16 v[126:129], v[144:147], v[188:191], v[126:129]
	v_mfma_f32_16x16x32_f16 v[122:125], v[152:155], v[188:191], v[122:125]
	v_mfma_f32_16x16x32_f16 v[118:121], v[144:147], v[208:211], v[118:121]
	v_mfma_f32_16x16x32_f16 v[114:117], v[152:155], v[208:211], v[114:117]
	v_mfma_f32_16x16x32_f16 v[102:105], v[144:147], v[216:219], v[102:105]
	v_mfma_f32_16x16x32_f16 v[98:101], v[152:155], v[216:219], v[98:101]
	v_mfma_f32_16x16x32_f16 v[86:89], v[144:147], v[224:227], v[86:89]
	v_mfma_f32_16x16x32_f16 v[82:85], v[152:155], v[224:227], v[82:85]
	v_mfma_f32_16x16x32_f16 v[126:129], v[148:151], v[192:195], v[126:129]
	v_mfma_f32_16x16x32_f16 v[122:125], v[156:159], v[192:195], v[122:125]
	v_mfma_f32_16x16x32_f16 v[118:121], v[148:151], v[212:215], v[118:121]
	v_mfma_f32_16x16x32_f16 v[114:117], v[156:159], v[212:215], v[114:117]
	v_mfma_f32_16x16x32_f16 v[102:105], v[148:151], v[220:223], v[102:105]
	v_mfma_f32_16x16x32_f16 v[98:101], v[156:159], v[220:223], v[98:101]
	v_mfma_f32_16x16x32_f16 v[86:89], v[148:151], v[228:231], v[86:89]
	v_mfma_f32_16x16x32_f16 v[82:85], v[156:159], v[228:231], v[82:85]
	s_setprio 0
	s_setprio 1
	v_mfma_f32_16x16x32_f16 v[110:113], v[160:163], v[188:191], v[110:113]
	v_mfma_f32_16x16x32_f16 v[106:109], v[180:183], v[188:191], v[106:109]
	v_mfma_f32_16x16x32_f16 v[94:97], v[160:163], v[208:211], v[94:97]
	v_mfma_f32_16x16x32_f16 v[90:93], v[180:183], v[208:211], v[90:93]
	v_mfma_f32_16x16x32_f16 v[78:81], v[160:163], v[216:219], v[78:81]
	v_mfma_f32_16x16x32_f16 v[74:77], v[180:183], v[216:219], v[74:77]
	v_mfma_f32_16x16x32_f16 v[70:73], v[160:163], v[224:227], v[70:73]
	v_mfma_f32_16x16x32_f16 v[66:69], v[180:183], v[224:227], v[66:69]
	v_mfma_f32_16x16x32_f16 v[110:113], v[164:167], v[192:195], v[110:113]
	v_mfma_f32_16x16x32_f16 v[106:109], v[184:187], v[192:195], v[106:109]
	v_mfma_f32_16x16x32_f16 v[94:97], v[164:167], v[212:215], v[94:97]
	v_mfma_f32_16x16x32_f16 v[90:93], v[184:187], v[212:215], v[90:93]
	v_mfma_f32_16x16x32_f16 v[78:81], v[164:167], v[220:223], v[78:81]
	v_mfma_f32_16x16x32_f16 v[74:77], v[184:187], v[220:223], v[74:77]
	v_mfma_f32_16x16x32_f16 v[70:73], v[164:167], v[228:231], v[70:73]
	v_mfma_f32_16x16x32_f16 v[66:69], v[184:187], v[228:231], v[66:69]
	s_setprio 0
	s_barrier
; #define PG8_STAGE(bufoff, gbase, voff) do { _Pragma("unroll") for (int _i = 0; _i < 2; ++_i) \
;         __builtin_amdgcn_global_load_lds((const unsigned*)((const char*)(gbase) + (voff)[_i]), (PG8_LAS unsigned*)(lds + (bufoff) + ldsw + _i * 8192), 16, 0, 0); } while (0)
; #define PG8_LDA(dst, b, h) do { _Pragma("unroll") for (int m = 0; m < 4; ++m) _Pragma("unroll") for (int k = 0; k < 2; ++k) dst[m][k] = *(const PG8_LAS half8*)(lds + PG8_SA(b, h) + aoff + m * 2048 + k * 1024); } while (0)
; #define PG8_MMA(ai, bj, At, Bt) do { __builtin_amdgcn_s_setprio(1); _Pragma("unroll") for (int m = 0; m < 4; ++m) _Pragma("unroll") for (int n = 0; n < 2; ++n) _Pragma("unroll") for (int k = 0; k < 2; ++k) \
;         acc[ai][bj][m][n] = __builtin_amdgcn_mfma_f32_16x16x32_f16(Bt[n][k], At[m][k], acc[ai][bj][m][n], 0, 0, 0); __builtin_amdgcn_s_setprio(0); } while (0)
; #define PG8_WAIT_V(n) asm volatile("s_waitcnt vmcnt(" #n ")" ::: "memory")
; #define PG8_WAIT_L(n) asm volatile("s_waitcnt lgkmcnt(" #n ")" ::: "memory")
; #define PG8_BAR __builtin_amdgcn_s_barrier()
; #define PG8_SCHED __builtin_amdgcn_sched_barrier(0)
; template <class Epi>
; __device__ __forceinline__ void gemm_phase(PG8_LAS unsigned char* lds, const Gemm g, const StaticOrder& S_, const Epi& E) {
;     ...
;             PG8_LDA(At, 1, 1); PG8_STAGE(PG8_SB(1, 0), b3, voffB); PG8_STAGE(PG8_SB(1, 1), b3 + hstepB, voffB); PG8_STAGE(PG8_SA(1, 0), a3, voffA);
;             PG8_WAIT_V(8); PG8_WAIT_L(0); PG8_BAR; PG8_MMA(1, 0, At, B0); PG8_MMA(1, 1, At, B1); PG8_BAR; PG8_SCHED;
;         }
	s_add_i32 s16, s33, s28
	v_lshl_add_u64 v[168:169], v[168:169], 0, s[86:87]
	s_mov_b32 m0, s16
	ds_read_b128 v[188:191], v143 offset:49152
	ds_read_b128 v[192:195], v143 offset:50176
	ds_read_b128 v[208:211], v143 offset:51200
	ds_read_b128 v[212:215], v143 offset:52224
	ds_read_b128 v[216:219], v143 offset:53248
	ds_read_b128 v[220:223], v143 offset:54272
	ds_read_b128 v[224:227], v143 offset:55296
	ds_read_b128 v[228:231], v143 offset:56320
	global_load_lds_dwordx4 v[168:169], off
	s_add_i32 m0, s16, 0x2000
	s_add_u32 s16, s18, 0xb0080
	v_lshl_add_u64 v[168:169], v[196:197], 0, s[86:87]
	s_addc_u32 s17, s19, 0
	s_add_i32 s18, s45, s28
	global_load_lds_dwordx4 v[168:169], off
	v_lshl_add_u64 v[168:169], s[16:17], 0, v[0:1]
	s_mov_b32 m0, s18
	s_nop 0
	global_load_lds_dwordx4 v[168:169], off
	v_lshl_add_u64 v[168:169], s[16:17], 0, v[134:135]
	s_add_i32 m0, s18, 0x2000
	s_nop 0
	global_load_lds_dwordx4 v[168:169], off
	v_lshl_add_u64 v[168:169], v[232:233], 0, s[86:87]
	s_mov_b32 m0, s35
	s_nop 0
	global_load_lds_dwordx4 v[168:169], off
	v_lshl_add_u64 v[168:169], v[234:235], 0, s[86:87]
	s_mov_b32 m0, s36
	s_nop 0
	global_load_lds_dwordx4 v[168:169], off
	s_waitcnt vmcnt(8)
	s_waitcnt lgkmcnt(0)
	s_barrier
	s_setprio 1
	s_waitcnt lgkmcnt(0)
	v_mfma_f32_16x16x32_f16 v[62:65], v[144:147], v[188:191], v[62:65]
	v_mfma_f32_16x16x32_f16 v[58:61], v[152:155], v[188:191], v[58:61]
	v_mfma_f32_16x16x32_f16 v[54:57], v[144:147], v[208:211], v[54:57]
	v_mfma_f32_16x16x32_f16 v[50:53], v[152:155], v[208:211], v[50:53]
	v_mfma_f32_16x16x32_f16 v[38:41], v[144:147], v[216:219], v[38:41]
	v_mfma_f32_16x16x32_f16 v[34:37], v[152:155], v[216:219], v[34:37]
	v_mfma_f32_16x16x32_f16 v[22:25], v[144:147], v[224:227], v[22:25]
	v_mfma_f32_16x16x32_f16 v[18:21], v[152:155], v[224:227], v[18:21]
	v_mfma_f32_16x16x32_f16 v[62:65], v[148:151], v[192:195], v[62:65]
	v_mfma_f32_16x16x32_f16 v[58:61], v[156:159], v[192:195], v[58:61]
	v_mfma_f32_16x16x32_f16 v[54:57], v[148:151], v[212:215], v[54:57]
	v_mfma_f32_16x16x32_f16 v[50:53], v[156:159], v[212:215], v[50:53]
	v_mfma_f32_16x16x32_f16 v[38:41], v[148:151], v[220:223], v[38:41]
	v_mfma_f32_16x16x32_f16 v[34:37], v[156:159], v[220:223], v[34:37]
	v_mfma_f32_16x16x32_f16 v[22:25], v[148:151], v[228:231], v[22:25]
	v_mfma_f32_16x16x32_f16 v[18:21], v[156:159], v[228:231], v[18:21]
	s_setprio 0
	s_setprio 1
	v_mfma_f32_16x16x32_f16 v[46:49], v[160:163], v[188:191], v[46:49]
	v_mfma_f32_16x16x32_f16 v[42:45], v[180:183], v[188:191], v[42:45]
	v_mfma_f32_16x16x32_f16 v[30:33], v[160:163], v[208:211], v[30:33]
	v_mfma_f32_16x16x32_f16 v[26:29], v[180:183], v[208:211], v[26:29]
	v_mfma_f32_16x16x32_f16 v[14:17], v[160:163], v[216:219], v[14:17]
	v_mfma_f32_16x16x32_f16 v[10:13], v[180:183], v[216:219], v[10:13]
	v_mfma_f32_16x16x32_f16 v[6:9], v[160:163], v[224:227], v[6:9]
	v_mfma_f32_16x16x32_f16 v[2:5], v[180:183], v[224:227], v[2:5]
	v_mfma_f32_16x16x32_f16 v[46:49], v[164:167], v[192:195], v[46:49]
	v_mfma_f32_16x16x32_f16 v[42:45], v[184:187], v[192:195], v[42:45]
	v_mfma_f32_16x16x32_f16 v[30:33], v[164:167], v[212:215], v[30:33]
	v_mfma_f32_16x16x32_f16 v[26:29], v[184:187], v[212:215], v[26:29]
	v_mfma_f32_16x16x32_f16 v[14:17], v[164:167], v[220:223], v[14:17]
	v_mfma_f32_16x16x32_f16 v[10:13], v[184:187], v[220:223], v[10:13]
	v_mfma_f32_16x16x32_f16 v[6:9], v[164:167], v[228:231], v[6:9]
	v_mfma_f32_16x16x32_f16 v[2:5], v[184:187], v[228:231], v[2:5]
	s_setprio 0
	s_add_i32 s44, s44, 2
	s_add_u32 s42, s42, 0x100
	s_addc_u32 s43, s43, 0
	s_cmp_gt_u32 s44, 41
	s_mov_b64 s[16:17], s[2:3]
	s_barrier
	s_cbranch_scc0 .LBB0_1475
	s_and_b64 vcc, exec, s[12:13]
	s_cbranch_vccz .LBB0_1478
	s_barrier
